# spatial-gating epilogue: per row-group load batching with counted waits
# baseline (speedup 1.0000x reference)
; template <int TRANS, class AP, class BP, class Epi>
; DI void mfma_gemm_tile(const AP& aptr, const BP& bptr, int m0, int n0, int K, const Epi& epi, bf16* lds) {
;     ...
;   for (int i = 0; i < 4; ++i) { ap[i] = aptr(m0 + lr + 32 * i) + lc; bp[i] = bptr(n0 + lr + 32 * i) + lc; }
;   f32x4 acc[4][4];
; #pragma unroll
;   for (int i = 0; i < 4; ++i)
; #pragma unroll
;     for (int j = 0; j < 4; ++j) acc[i][j] = f32x4{0.f, 0.f, 0.f, 0.f};
;   const int nk = K >> 6;
;     ...
;   GEMM_STAGE(0, 0);
;   if (nk > 1) GEMM_STAGE(1, 1);
;   const unsigned lbase = (unsigned)(size_t)lds;
;   const unsigned sw0 = (unsigned)(((lq ^ (l16 & 7)) * 8) * 2), sw1 = (unsigned)((((4 + lq) ^ (l16 & 7)) * 8) * 2);
;   const unsigned a_row = (unsigned)((wm + l16) * 128), b_row = (unsigned)((128 * 64 + (wn + l16) * 64) * 2);
;     ...
;   for (int ks = 0; ks < nk; ++ks) {
;     if (ks + 1 < nk) asm volatile("s_waitcnt vmcnt(8)\n\ts_barrier" ::: "memory");
;     else asm volatile("s_waitcnt vmcnt(0)\n\ts_barrier" ::: "memory");
;     const unsigned sb_ = lbase + (unsigned)((ks & 1) * (2 * 128 * 64) * 2);
;     const unsigned a0 = sb_ + a_row + sw0, a1 = sb_ + a_row + sw1, b0 = sb_ + b_row + sw0, b1 = sb_ + b_row + sw1;
;     bf16x8 af[2][4], bfr[2][4];
;     LDSR(af[0][0], a0, 0); LDSR(af[0][1], a0, 2048); LDSR(af[0][2], a0, 4096); LDSR(af[0][3], a0, 6144);
;     LDSR(bfr[0][0], b0, 0); LDSR(bfr[0][1], b0, 2048); LDSR(bfr[0][2], b0, 4096); LDSR(bfr[0][3], b0, 6144);
;     LDSR(af[1][0], a1, 0); LDSR(af[1][1], a1, 2048); LDSR(af[1][2], a1, 4096); LDSR(af[1][3], a1, 6144);
;     LDSR(bfr[1][0], b1, 0); LDSR(bfr[1][1], b1, 2048); LDSR(bfr[1][2], b1, 4096); LDSR(bfr[1][3], b1, 6144);
;     asm volatile("s_waitcnt lgkmcnt(0)" : "+v"(af[0][0]), "+v"(af[0][1]), "+v"(af[0][2]), "+v"(af[0][3]), "+v"(bfr[0][0]), "+v"(bfr[0][1]), "+v"(bfr[0][2]), "+v"(bfr[0][3]),
;                  "+v"(af[1][0]), "+v"(af[1][1]), "+v"(af[1][2]), "+v"(af[1][3]), "+v"(bfr[1][0]), "+v"(bfr[1][1]), "+v"(bfr[1][2]), "+v"(bfr[1][3]) : : "memory");
; DI void phase_odd_b(const Ctx& c, int l, bf16* lds) {
;     ...
;       const int ti = it - n_s1, g = ti & 3, row0 = (ti >> 2) * 128;
;       mfma_gemm_tile<0>(RowPtr{c.WL() + WL_SGU / 2 + (size_t)g * 128 * 128, 128}, RowPtr{c.VGT() + (size_t)ti * 128 * 128, 128}, 0, 0, 128,
;                         EpiSgu{c.P(), c.HY(), p.sgu_b + (li * 4 + g) * 128, row0, g}, lds);
.LBB0_379:
	s_andn2_b64 vcc, exec, s[0:1]
	s_cbranch_vccnz .LBB0_381
	s_add_i32 s34, s13, 0xfffffc00
	s_and_b32 s16, s12, 3
	s_lshl_b32 s0, s34, 5
	s_and_b32 s17, s0, 0x7fffff80
	s_lshl_b32 s0, s16, 15
	v_readlane_b32 s2, v253, 15
	s_mov_b32 s35, s85
	v_readlane_b32 s3, v253, 16
	s_add_u32 s18, s2, s0
	s_addc_u32 s19, s3, 0
	s_lshl_b64 s[0:1], s[34:35], 15
	v_readlane_b32 s2, v253, 13
	v_mov_b32_e32 v20, v172
	s_add_u32 s20, s2, s0
	v_readlane_b32 s0, v253, 14
	s_addc_u32 s21, s0, s1
	v_ashrrev_i32_e32 v2, 3, v20
	s_or_b32 s0, s16, s11
	v_readlane_b32 s24, v252, 4
	v_xor_b32_e32 v0, v2, v20
	s_lshl_b32 s0, s0, 9
	v_readlane_b32 s30, v252, 10
	v_lshlrev_b32_e32 v0, 4, v0
	v_readlane_b32 s31, v252, 11
	s_add_u32 s0, s30, s0
	v_readfirstlane_b32 s22, v20
	v_and_b32_e32 v0, 0x70, v0
	s_addc_u32 s1, s31, 0
	v_lshl_add_u64 v[4:5], s[18:19], 0, v[0:1]
	v_ashrrev_i32_e32 v3, 31, v2
	s_lshl_b32 s19, s22, 4
	v_lshlrev_b64 v[2:3], 8, v[2:3]
	s_and_b32 s19, s19, 0xfffffc00
	v_lshl_add_u64 v[6:7], s[20:21], 0, v[0:1]
	v_lshl_add_u64 v[8:9], v[4:5], 0, v[2:3]
	s_mov_b64 s[2:3], 0x2000
	s_mov_b32 m0, s19
	v_lshl_add_u64 v[10:11], v[6:7], 0, v[2:3]
	v_lshl_add_u64 v[12:13], v[2:3], 0, s[2:3]
	global_load_lds_dwordx4 v[8:9], off
	s_add_i32 m0, s19, 0x4000
	v_lshl_add_u64 v[14:15], v[4:5], 0, v[12:13]
	s_mov_b64 s[2:3], 0x4000
	global_load_lds_dwordx4 v[10:11], off
	s_add_i32 m0, s19, 0x1000
	v_lshl_add_u64 v[12:13], v[6:7], 0, v[12:13]
	v_lshl_add_u64 v[16:17], v[2:3], 0, s[2:3]
	global_load_lds_dwordx4 v[14:15], off
	s_add_i32 m0, s19, 0x5000
	v_lshl_add_u64 v[18:19], v[4:5], 0, v[16:17]
	s_mov_b64 s[2:3], 0x6000
	global_load_lds_dwordx4 v[12:13], off
	s_add_i32 m0, s19, 0x2000
	v_lshl_add_u64 v[16:17], v[6:7], 0, v[16:17]
	v_lshl_add_u64 v[2:3], v[2:3], 0, s[2:3]
	global_load_lds_dwordx4 v[18:19], off
	s_add_i32 m0, s19, 0x6000
	v_lshl_add_u64 v[4:5], v[4:5], 0, v[2:3]
	global_load_lds_dwordx4 v[16:17], off
	s_add_i32 m0, s19, 0x3000
	v_lshl_add_u64 v[2:3], v[6:7], 0, v[2:3]
	global_load_lds_dwordx4 v[4:5], off
	s_add_i32 m0, s19, 0x7000
	s_mov_b64 s[2:3], 0x80
	global_load_lds_dwordx4 v[2:3], off
	v_lshl_add_u64 v[6:7], v[8:9], 0, s[2:3]
	s_add_i32 m0, s19, 0x8000
	s_ashr_i32 s23, s22, 1
	global_load_lds_dwordx4 v[6:7], off
	v_lshl_add_u64 v[6:7], v[10:11], 0, s[2:3]
	s_add_i32 m0, s19, 0xc000
	v_lshl_add_u64 v[4:5], v[4:5], 0, s[2:3]
	global_load_lds_dwordx4 v[6:7], off
	v_lshl_add_u64 v[6:7], v[14:15], 0, s[2:3]
	s_add_i32 m0, s19, 0x9000
	s_andn2_b32 s23, s23, 63
	global_load_lds_dwordx4 v[6:7], off
	v_lshl_add_u64 v[6:7], v[12:13], 0, s[2:3]
	s_add_i32 m0, s19, 0xd000
	v_and_b32_e32 v0, 15, v20
	global_load_lds_dwordx4 v[6:7], off
	v_lshl_add_u64 v[6:7], v[18:19], 0, s[2:3]
	s_add_i32 m0, s19, 0xa000
	s_and_b32 s18, s22, 64
	global_load_lds_dwordx4 v[6:7], off
	v_lshl_add_u64 v[6:7], v[16:17], 0, s[2:3]
	s_add_i32 m0, s19, 0xe000
	v_lshl_add_u64 v[2:3], v[2:3], 0, s[2:3]
	global_load_lds_dwordx4 v[6:7], off
	s_add_i32 m0, s19, 0xb000
	v_lshrrev_b32_e32 v21, 4, v20
	global_load_lds_dwordx4 v[4:5], off
	s_add_i32 m0, s19, 0xf000
	v_bfe_u32 v140, v20, 4, 2
	global_load_lds_dwordx4 v[2:3], off
	v_and_b32_e32 v2, 7, v20
	v_or_b32_e32 v62, s23, v0
	v_or_b32_e32 v0, s18, v0
	v_bitop3_b32 v3, v21, v2, 3 bitop3:0x6c
	v_bitop3_b32 v2, v140, v2, 4 bitop3:0x36
	v_lshlrev_b32_e32 v0, 7, v0
	v_lshlrev_b32_e32 v63, 4, v3
	v_lshlrev_b32_e32 v104, 4, v2
	v_lshlrev_b32_e32 v105, 7, v62
	v_or_b32_e32 v2, 0x4000, v0
	v_or_b32_e32 v18, v105, v63
	v_or_b32_e32 v50, v105, v104
	v_or_b32_e32 v34, v2, v63
	s_waitcnt vmcnt(8)
	s_barrier
	v_or_b32_e32 v68, v2, v104
	ds_read_b128 v[2:5], v18 offset:0
	ds_read_b128 v[6:9], v18 offset:0x800
	ds_read_b128 v[10:13], v18 offset:0x1000
	ds_read_b128 v[14:17], v18 offset:0x1800
	ds_read_b128 v[18:21], v34 offset:0
	ds_read_b128 v[22:25], v34 offset:0x800
	ds_read_b128 v[26:29], v34 offset:0x1000
	ds_read_b128 v[30:33], v34 offset:0x1800
	ds_read_b128 v[34:37], v50 offset:0
	ds_read_b128 v[38:41], v50 offset:0x800
	ds_read_b128 v[42:45], v50 offset:0x1000
	ds_read_b128 v[46:49], v50 offset:0x1800
	ds_read_b128 v[50:53], v68 offset:0
	ds_read_b128 v[54:57], v68 offset:0x800
	ds_read_b128 v[58:61], v68 offset:0x1000
	ds_read_b128 v[64:67], v68 offset:0x1800
	v_or_b32_e32 v0, 0xc000, v0
	s_waitcnt lgkmcnt(0)
	s_waitcnt vmcnt(0)
	s_barrier
; template <int TRANS, class AP, class BP, class Epi>
; DI void mfma_gemm_tile(const AP& aptr, const BP& bptr, int m0, int n0, int K, const Epi& epi, bf16* lds) {
;     ...
; #pragma unroll
;     for (int kk = 0; kk < 2; ++kk)
; #pragma unroll
;       for (int i = 0; i < 4; ++i)
; #pragma unroll
;         for (int j = 0; j < 4; ++j)
;           acc[i][j] = TRANS ? __builtin_amdgcn_mfma_f32_16x16x32_bf16(af[kk][i], bfr[kk][j], acc[i][j], 0, 0, 0)
;                             : __builtin_amdgcn_mfma_f32_16x16x32_bf16(bfr[kk][j], af[kk][i], acc[i][j], 0, 0, 0);
	s_lshl_b32 s34, s16, 8
	v_mfma_f32_16x16x32_bf16 v[68:71], v[18:21], v[2:5], 0
	s_movk_i32 s2, 0x1000
	s_mov_b32 s3, 0x3ea7ba05
	s_mov_b32 s16, 0xbfb8aa3b
	v_mfma_f32_16x16x32_bf16 v[72:75], v[22:25], v[2:5], 0
	s_mov_b32 s20, 0x3f87dc22
	s_mov_b32 s22, 0x3fb5f0e3
	v_readlane_b32 s25, v252, 5
	v_mfma_f32_16x16x32_bf16 v[76:79], v[26:29], v[2:5], 0
	v_readlane_b32 s26, v252, 6
	s_mov_b32 s24, 0xbe91a98e
	v_readlane_b32 s27, v252, 7
	v_mfma_f32_16x16x32_bf16 v[2:5], v[30:33], v[2:5], 0
	s_mov_b32 s26, 0x3e827906
	v_readlane_b32 s28, v252, 8
	v_readlane_b32 s29, v252, 9
	v_mfma_f32_16x16x32_bf16 v[80:83], v[18:21], v[6:9], 0
	v_mfma_f32_16x16x32_bf16 v[84:87], v[22:25], v[6:9], 0
	v_mfma_f32_16x16x32_bf16 v[88:91], v[26:29], v[6:9], 0
	v_mfma_f32_16x16x32_bf16 v[6:9], v[30:33], v[6:9], 0
	v_mfma_f32_16x16x32_bf16 v[92:95], v[18:21], v[10:13], 0
	v_mfma_f32_16x16x32_bf16 v[96:99], v[22:25], v[10:13], 0
	v_mfma_f32_16x16x32_bf16 v[100:103], v[26:29], v[10:13], 0
	v_mfma_f32_16x16x32_bf16 v[10:13], v[30:33], v[10:13], 0
	v_mfma_f32_16x16x32_bf16 v[22:25], v[22:25], v[14:17], 0
	v_mfma_f32_16x16x32_bf16 v[26:29], v[26:29], v[14:17], 0
	v_mfma_f32_16x16x32_bf16 v[18:21], v[18:21], v[14:17], 0
	v_mfma_f32_16x16x32_bf16 v[14:17], v[30:33], v[14:17], 0
	v_mfma_f32_16x16x32_bf16 v[30:33], v[50:53], v[34:37], v[68:71]
	v_mfma_f32_16x16x32_bf16 v[68:71], v[54:57], v[34:37], v[72:75]
	v_mfma_f32_16x16x32_bf16 v[72:75], v[58:61], v[34:37], v[76:79]
	v_mfma_f32_16x16x32_bf16 v[2:5], v[64:67], v[34:37], v[2:5]
	v_mfma_f32_16x16x32_bf16 v[34:37], v[50:53], v[38:41], v[80:83]
	v_mfma_f32_16x16x32_bf16 v[76:79], v[54:57], v[38:41], v[84:87]
	v_mfma_f32_16x16x32_bf16 v[80:83], v[58:61], v[38:41], v[88:91]
	v_mfma_f32_16x16x32_bf16 v[6:9], v[64:67], v[38:41], v[6:9]
	v_mfma_f32_16x16x32_bf16 v[38:41], v[50:53], v[42:45], v[92:95]
	v_mfma_f32_16x16x32_bf16 v[84:87], v[54:57], v[42:45], v[96:99]
	v_mfma_f32_16x16x32_bf16 v[88:91], v[58:61], v[42:45], v[100:103]
	v_mfma_f32_16x16x32_bf16 v[10:13], v[64:67], v[42:45], v[10:13]
	v_add_u32_e32 v42, 0x8000, v105
	v_or_b32_e32 v116, v42, v104
	v_mfma_f32_16x16x32_bf16 v[22:25], v[54:57], v[46:49], v[22:25]
	v_mfma_f32_16x16x32_bf16 v[26:29], v[58:61], v[46:49], v[26:29]
	v_or_b32_e32 v58, v42, v63
	v_or_b32_e32 v63, v0, v63
	v_or_b32_e32 v0, v0, v104
	v_mfma_f32_16x16x32_bf16 v[18:21], v[50:53], v[46:49], v[18:21]
	ds_read_b128 v[42:45], v58 offset:0
	v_mfma_f32_16x16x32_bf16 v[14:17], v[64:67], v[46:49], v[14:17]
	ds_read_b128 v[46:49], v58 offset:0x800
	ds_read_b128 v[50:53], v58 offset:0x1000
	ds_read_b128 v[54:57], v58 offset:0x1800
	ds_read_b128 v[58:61], v63 offset:0
	ds_read_b128 v[64:67], v63 offset:0x800
	ds_read_b128 v[92:95], v63 offset:0x1000
	ds_read_b128 v[96:99], v63 offset:0x1800
	ds_read_b128 v[100:103], v116 offset:0
	ds_read_b128 v[104:107], v116 offset:0x800
	ds_read_b128 v[108:111], v116 offset:0x1000
	ds_read_b128 v[112:115], v116 offset:0x1800
	ds_read_b128 v[116:119], v0 offset:0
	ds_read_b128 v[120:123], v0 offset:0x800
	ds_read_b128 v[124:127], v0 offset:0x1000
	ds_read_b128 v[128:131], v0 offset:0x1800
	v_ashrrev_i32_e32 v63, 31, v62
	s_waitcnt lgkmcnt(0)
	s_nop 0
	v_mfma_f32_16x16x32_bf16 v[30:33], v[58:61], v[42:45], v[30:33]
	v_mfma_f32_16x16x32_bf16 v[68:71], v[64:67], v[42:45], v[68:71]
	v_mfma_f32_16x16x32_bf16 v[72:75], v[92:95], v[42:45], v[72:75]
	v_mfma_f32_16x16x32_bf16 v[2:5], v[96:99], v[42:45], v[2:5]
	v_mfma_f32_16x16x32_bf16 v[42:45], v[64:67], v[46:49], v[76:79]
	v_mfma_f32_16x16x32_bf16 v[84:87], v[64:67], v[50:53], v[84:87]
	v_mfma_f32_16x16x32_bf16 v[10:13], v[96:99], v[50:53], v[10:13]
	v_mfma_f32_16x16x32_bf16 v[64:67], v[64:67], v[54:57], v[22:25]
	v_mfma_f32_16x16x32_bf16 v[34:37], v[58:61], v[46:49], v[34:37]
	v_mfma_f32_16x16x32_bf16 v[76:79], v[92:95], v[46:49], v[80:83]
	v_mfma_f32_16x16x32_bf16 v[80:83], v[58:61], v[50:53], v[38:41]
	v_mfma_f32_16x16x32_bf16 v[132:135], v[58:61], v[54:57], v[18:21]
	v_mfma_f32_16x16x32_bf16 v[58:61], v[120:123], v[100:103], v[68:71]
	v_mfma_f32_16x16x32_bf16 v[18:21], v[128:131], v[108:111], v[10:13]
	s_nop 1
	v_mov_b64_e32 v[68:69], s[62:63]
	v_mfma_f32_16x16x32_bf16 v[10:13], v[120:123], v[112:115], v[64:67]
	s_nop 2
	v_add_u32_e32 v66, s17, v62
	v_lshl_add_u64 v[64:65], v[62:63], 2, s[0:1]
	v_mad_i64_i32 v[62:63], s[0:1], v66, s78, v[68:69]
	s_lshl_b32 s0, s18, 1
	v_lshl_add_u64 v[62:63], v[62:63], 0, s[34:35]
	v_lshl_or_b32 v0, v140, 3, s0
	v_mfma_f32_16x16x32_bf16 v[6:9], v[96:99], v[46:49], v[6:9]
	global_load_dword v70, v[64:65], off
	s_mov_b32 s18, 0x3f3504f3
	s_mov_b32 s0, 0xbfba00e3
	v_mfma_f32_16x16x32_bf16 v[88:91], v[92:95], v[50:53], v[88:91]
	s_brev_b32 s17, -2
	v_ashrrev_i32_e32 v67, 31, v66
	v_mfma_f32_16x16x32_bf16 v[92:95], v[92:95], v[54:57], v[26:29]
	v_mfma_f32_16x16x32_bf16 v[96:99], v[96:99], v[54:57], v[14:17]
	v_mfma_f32_16x16x32_bf16 v[54:57], v[124:127], v[100:103], v[72:75]
	s_nop 2
	v_lshl_add_u64 v[74:75], v[62:63], 0, v[0:1]
	v_mfma_f32_16x16x32_bf16 v[38:41], v[124:127], v[104:107], v[76:79]
	v_add_co_u32_e32 v72, vcc, s2, v74
	s_nop 1
	global_load_dwordx2 v[76:77], v[74:75], off offset:2048
	v_addc_co_u32_e32 v73, vcc, 0, v75, vcc
	global_load_dwordx2 v[192:193], v[72:73], off
	global_load_dword v194, v[64:65], off
	global_load_dwordx2 v[196:197], v[74:75], off offset:2080
	global_load_dwordx2 v[198:199], v[72:73], off offset:32
	global_load_dword v200, v[64:65], off
	global_load_dwordx2 v[202:203], v[74:75], off offset:2112
	global_load_dwordx2 v[204:205], v[72:73], off offset:64
	global_load_dword v206, v[64:65], off
	global_load_dwordx2 v[208:209], v[74:75], off offset:2144
	global_load_dwordx2 v[210:211], v[72:73], off offset:96
	v_mfma_f32_16x16x32_bf16 v[136:139], v[116:119], v[100:103], v[30:33]
	s_waitcnt vmcnt(9)
; DI float erf_as(float x) {
;   const float ax = fabsf(x);
;   const float t = __builtin_amdgcn_rcpf(1.f + 0.3275911f * ax);
;   const float poly = t * (0.254829592f + t * (-0.284496736f + t * (1.421413741f + t * (-1.453152027f + t * 1.061405429f))));
;   const float y = 1.f - poly * __builtin_amdgcn_exp2f(-1.4426950408889634f * ax * ax);
;   return copysignf(y, x);
; }
; DI float gelu(float x) { return 0.5f * x * (1.f + erf_as(x * 0.70710678118654752f)); }
	v_lshlrev_b32_e32 v62, 16, v76
	v_and_b32_e32 v63, 0xffff0000, v76
	v_mfma_f32_16x16x32_bf16 v[30:33], v[116:119], v[108:111], v[80:83]
	s_nop 2
	v_mul_f32_e64 v82, v62, s18
	v_mul_f32_e64 v83, v63, s18
	v_mfma_f32_16x16x32_bf16 v[26:29], v[120:123], v[108:111], v[84:87]
	v_fma_f32 v71, |v82|, s3, 1.0
	v_lshlrev_b32_e32 v80, 16, v192
	v_and_b32_e32 v81, 0xffff0000, v192
	v_rcp_f32_e32 v84, v71
	v_mul_f32_e64 v71, |v82|, s16
	v_mul_f32_e64 v71, |v82|, v71
	v_exp_f32_e32 v86, v71
	v_mul_f32_e32 v71, 0xbfb8aa3b, v80
	v_exp_f32_e32 v71, v71
	v_mfma_f32_16x16x32_bf16 v[22:25], v[124:127], v[108:111], v[88:91]
	v_lshlrev_b32_e32 v78, 16, v193
	v_and_b32_e32 v79, 0xffff0000, v193
	v_add_f32_e32 v71, 1.0, v71
	v_pk_mul_f32 v[90:91], v[62:63], 0.5 op_sel_hi:[1,0]
	v_fma_f32 v62, |v83|, s3, 1.0
	v_rcp_f32_e32 v85, v62
	v_rcp_f32_e32 v88, v71
	v_mov_b64_e32 v[62:63], s[0:1]
	v_mul_f32_e64 v71, |v83|, s16
	v_mfma_f32_16x16x32_bf16 v[46:49], v[116:119], v[104:107], v[34:37]
	v_mul_f32_e64 v71, |v83|, v71
	v_exp_f32_e32 v87, v71
	v_mfma_f32_16x16x32_bf16 v[34:37], v[128:131], v[104:107], v[6:9]
	v_mfma_f32_16x16x32_bf16 v[6:9], v[124:127], v[112:115], v[92:95]
	s_nop 2
	v_fma_f32 v92, v84, s20, v62
	v_fma_f32 v93, v85, s20, v62
	v_mfma_f32_16x16x32_bf16 v[50:53], v[128:131], v[100:103], v[2:5]
	v_fma_f32 v92, v84, v92, s22
	v_fma_f32 v93, v85, v93, s22
	v_pk_fma_f32 v[92:93], v[84:85], v[92:93], s[24:25] op_sel_hi:[1,1,0]
	v_mfma_f32_16x16x32_bf16 v[42:45], v[120:123], v[104:107], v[42:45]
	v_fma_f32 v92, v84, v92, s26
	v_fma_f32 v93, v85, v93, s26
	v_pk_mul_f32 v[84:85], v[84:85], v[92:93]
	v_mfma_f32_16x16x32_bf16 v[14:17], v[116:119], v[112:115], v[132:135]
	v_fma_f32 v84, -v86, v84, 1.0
	v_fma_f32 v85, -v87, v85, 1.0
	v_bfi_b32 v83, s17, v85, v83
	v_bfi_b32 v82, s17, v84, v82
	v_pk_add_f32 v[84:85], v[136:137], v[70:71] op_sel_hi:[1,0]
	v_mul_f32_e32 v71, 0xbfb8aa3b, v81
	v_exp_f32_e32 v71, v71
	v_pk_add_f32 v[82:83], v[82:83], 1.0 op_sel_hi:[1,0]
	v_mfma_f32_16x16x32_bf16 v[2:5], v[128:131], v[112:115], v[96:99]
	v_mul_f32_e64 v82, v90, v82
	v_mul_f32_e64 v83, v91, v83
	v_add_f32_e32 v71, 1.0, v71
	v_rcp_f32_e32 v89, v71
	v_pk_mul_f32 v[82:83], v[84:85], v[82:83]
	v_pk_mul_f32 v[80:81], v[88:89], v[80:81]
	s_nop 0
	v_pk_mul_f32 v[80:81], v[80:81], v[82:83]
	s_nop 0
	v_cvt_pk_bf16_f32 v76, v80, v81
	v_lshlrev_b32_e32 v80, 16, v77
	v_and_b32_e32 v81, 0xffff0000, v77
	v_pk_mul_f32 v[82:83], v[80:81], s[18:19] op_sel_hi:[1,0]
	v_mul_f32_e32 v77, 0xbfb8aa3b, v79
	v_fma_f32 v71, |v82|, s3, 1.0
	v_rcp_f32_e32 v84, v71
	v_mul_f32_e64 v71, |v82|, s16
	v_mul_f32_e64 v71, |v82|, v71
	v_exp_f32_e32 v86, v71
	v_mul_f32_e32 v71, 0xbfb8aa3b, v78
	v_exp_f32_e32 v71, v71
	v_exp_f32_e32 v77, v77
	v_pk_mul_f32 v[80:81], v[80:81], 0.5 op_sel_hi:[1,0]
	v_add_f32_e32 v71, 1.0, v71
	v_rcp_f32_e32 v88, v71
	v_fma_f32 v71, |v83|, s3, 1.0
	v_rcp_f32_e32 v85, v71
	v_mul_f32_e64 v71, |v83|, s16
	v_mul_f32_e64 v71, |v83|, v71
	v_exp_f32_e32 v87, v71
	v_pk_fma_f32 v[90:91], v[84:85], s[20:21], v[62:63] op_sel_hi:[1,0,0]
	v_add_f32_e32 v77, 1.0, v77
	v_pk_fma_f32 v[90:91], v[84:85], v[90:91], s[22:23] op_sel_hi:[1,1,0]
	v_rcp_f32_e32 v89, v77
	v_pk_fma_f32 v[90:91], v[84:85], v[90:91], s[24:25] op_sel_hi:[1,1,0]
	v_pk_add_f32 v[70:71], v[138:139], v[70:71] op_sel_hi:[1,0]
	v_pk_fma_f32 v[90:91], v[84:85], v[90:91], s[26:27] op_sel_hi:[1,1,0]
	v_pk_mul_f32 v[78:79], v[88:89], v[78:79]
	v_pk_mul_f32 v[84:85], v[84:85], v[90:91]
	s_nop 0
	v_pk_fma_f32 v[84:85], v[86:87], v[84:85], 1.0 op_sel_hi:[1,1,0] neg_lo:[1,0,0] neg_hi:[1,0,0]
	s_nop 0
	v_bfi_b32 v83, s17, v85, v83
	v_bfi_b32 v82, s17, v84, v82
	v_pk_add_f32 v[82:83], v[82:83], 1.0 op_sel_hi:[1,0]
	s_nop 0
	v_pk_mul_f32 v[80:81], v[80:81], v[82:83]
	s_nop 0
	v_pk_mul_f32 v[70:71], v[70:71], v[80:81]
	s_nop 0
	v_pk_mul_f32 v[70:71], v[78:79], v[70:71]
	s_nop 0
	v_cvt_pk_bf16_f32 v77, v70, v71
	v_lshlrev_b64 v[70:71], 11, v[66:67]
	v_lshl_add_u64 v[70:71], s[60:61], 0, v[70:71]
	v_lshl_add_u64 v[70:71], v[70:71], 0, s[34:35]
	v_lshl_add_u64 v[70:71], v[70:71], 0, v[0:1]
	global_store_dwordx2 v[70:71], v[76:77], off offset:1024
	s_nop 0
	s_waitcnt vmcnt(7)
	v_pk_add_f32 v[58:59], v[58:59], v[194:195] op_sel_hi:[1,0]
	v_lshlrev_b32_e32 v82, 16, v196
	v_and_b32_e32 v83, 0xffff0000, v196
	v_pk_mul_f32 v[86:87], v[82:83], s[18:19] op_sel_hi:[1,0]
	v_lshlrev_b32_e32 v84, 16, v198
	v_fma_f32 v67, |v86|, s3, 1.0
	v_rcp_f32_e32 v88, v67
	v_mul_f32_e64 v67, |v86|, s16
	v_mul_f32_e64 v67, |v86|, v67
	v_exp_f32_e32 v90, v67
	v_mul_f32_e32 v67, 0xbfb8aa3b, v84
	v_exp_f32_e32 v67, v67
	v_and_b32_e32 v85, 0xffff0000, v198
	v_pk_mul_f32 v[82:83], v[82:83], 0.5 op_sel_hi:[1,0]
	v_lshlrev_b32_e32 v78, 16, v197
	v_add_f32_e32 v67, 1.0, v67
	v_rcp_f32_e32 v92, v67
	v_fma_f32 v67, |v87|, s3, 1.0
	v_rcp_f32_e32 v89, v67
	v_mul_f32_e64 v67, |v87|, s16
	v_mul_f32_e64 v67, |v87|, v67
	v_exp_f32_e32 v91, v67
	v_mul_f32_e32 v67, 0xbfb8aa3b, v85
	v_pk_fma_f32 v[94:95], v[88:89], s[20:21], v[62:63] op_sel_hi:[1,0,0]
	v_exp_f32_e32 v67, v67
	v_pk_fma_f32 v[94:95], v[88:89], v[94:95], s[22:23] op_sel_hi:[1,1,0]
	v_and_b32_e32 v79, 0xffff0000, v197
	v_pk_fma_f32 v[94:95], v[88:89], v[94:95], s[24:25] op_sel_hi:[1,1,0]
	v_add_f32_e32 v67, 1.0, v67
	v_pk_fma_f32 v[94:95], v[88:89], v[94:95], s[26:27] op_sel_hi:[1,1,0]
	v_rcp_f32_e32 v93, v67
	v_pk_mul_f32 v[88:89], v[88:89], v[94:95]
	v_lshlrev_b32_e32 v80, 16, v199
	v_pk_fma_f32 v[88:89], v[90:91], v[88:89], 1.0 op_sel_hi:[1,1,0] neg_lo:[1,0,0] neg_hi:[1,0,0]
	v_and_b32_e32 v81, 0xffff0000, v199
	v_bfi_b32 v87, s17, v89, v87
	v_bfi_b32 v86, s17, v88, v86
	v_pk_add_f32 v[86:87], v[86:87], 1.0 op_sel_hi:[1,0]
	v_pk_add_f32 v[60:61], v[60:61], v[194:195] op_sel_hi:[1,0]
	v_pk_mul_f32 v[82:83], v[82:83], v[86:87]
	s_nop 0
	v_pk_mul_f32 v[58:59], v[58:59], v[82:83]
	v_pk_mul_f32 v[82:83], v[92:93], v[84:85]
	s_nop 0
	v_pk_mul_f32 v[58:59], v[82:83], v[58:59]
	v_pk_mul_f32 v[82:83], v[78:79], s[18:19] op_sel_hi:[1,0]
	v_cvt_pk_bf16_f32 v58, v58, v59
	v_fma_f32 v59, |v82|, s3, 1.0
	v_rcp_f32_e32 v84, v59
	v_mul_f32_e64 v59, |v82|, s16
	v_mul_f32_e64 v59, |v82|, v59
	v_exp_f32_e32 v86, v59
	v_mul_f32_e32 v59, 0xbfb8aa3b, v80
	v_exp_f32_e32 v59, v59
	v_pk_mul_f32 v[78:79], v[78:79], 0.5 op_sel_hi:[1,0]
	v_add_f32_e32 v59, 1.0, v59
	v_rcp_f32_e32 v88, v59
	v_fma_f32 v59, |v83|, s3, 1.0
	v_rcp_f32_e32 v85, v59
	v_mul_f32_e64 v59, |v83|, s16
	v_mul_f32_e64 v59, |v83|, v59
	v_exp_f32_e32 v87, v59
	v_mul_f32_e32 v59, 0xbfb8aa3b, v81
	v_pk_fma_f32 v[90:91], v[84:85], s[20:21], v[62:63] op_sel_hi:[1,0,0]
	v_exp_f32_e32 v59, v59
	v_pk_fma_f32 v[90:91], v[84:85], v[90:91], s[22:23] op_sel_hi:[1,1,0]
	v_add_f32_e32 v59, 1.0, v59
	v_pk_fma_f32 v[90:91], v[84:85], v[90:91], s[24:25] op_sel_hi:[1,1,0]
	v_rcp_f32_e32 v89, v59
	v_pk_fma_f32 v[90:91], v[84:85], v[90:91], s[26:27] op_sel_hi:[1,1,0]
	v_pk_mul_f32 v[76:77], v[88:89], v[80:81]
	v_pk_mul_f32 v[84:85], v[84:85], v[90:91]
	s_nop 0
	v_pk_fma_f32 v[84:85], v[86:87], v[84:85], 1.0 op_sel_hi:[1,1,0] neg_lo:[1,0,0] neg_hi:[1,0,0]
	s_nop 0
	v_bfi_b32 v83, s17, v85, v83
	v_bfi_b32 v82, s17, v84, v82
	v_pk_add_f32 v[82:83], v[82:83], 1.0 op_sel_hi:[1,0]
	s_nop 0
	v_pk_mul_f32 v[78:79], v[78:79], v[82:83]
	s_nop 0
	v_pk_mul_f32 v[60:61], v[60:61], v[78:79]
	s_nop 0
	v_pk_mul_f32 v[60:61], v[76:77], v[60:61]
	s_nop 0
	v_cvt_pk_bf16_f32 v59, v60, v61
	global_store_dwordx2 v[70:71], v[58:59], off offset:1056
	s_nop 0
	s_waitcnt vmcnt(5)
	v_lshlrev_b32_e32 v78, 16, v202
	v_and_b32_e32 v79, 0xffff0000, v202
	v_pk_mul_f32 v[82:83], v[78:79], s[18:19] op_sel_hi:[1,0]
	v_lshlrev_b32_e32 v80, 16, v204
	v_fma_f32 v59, |v82|, s3, 1.0
	v_rcp_f32_e32 v84, v59
	v_mul_f32_e64 v59, |v82|, s16
	v_mul_f32_e64 v59, |v82|, v59
	v_exp_f32_e32 v86, v59
	v_mul_f32_e32 v59, 0xbfb8aa3b, v80
	v_exp_f32_e32 v59, v59
	v_and_b32_e32 v81, 0xffff0000, v204
	v_pk_mul_f32 v[78:79], v[78:79], 0.5 op_sel_hi:[1,0]
	v_lshlrev_b32_e32 v60, 16, v203
	v_add_f32_e32 v59, 1.0, v59
	v_rcp_f32_e32 v88, v59
	v_fma_f32 v59, |v83|, s3, 1.0
	v_rcp_f32_e32 v85, v59
	v_mul_f32_e64 v59, |v83|, s16
	v_mul_f32_e64 v59, |v83|, v59
	v_exp_f32_e32 v87, v59
	v_pk_add_f32 v[54:55], v[54:55], v[200:201] op_sel_hi:[1,0]
	v_mul_f32_e32 v59, 0xbfb8aa3b, v81
	v_pk_fma_f32 v[90:91], v[84:85], s[20:21], v[62:63] op_sel_hi:[1,0,0]
	v_exp_f32_e32 v59, v59
	v_pk_fma_f32 v[90:91], v[84:85], v[90:91], s[22:23] op_sel_hi:[1,1,0]
	v_and_b32_e32 v61, 0xffff0000, v203
	v_pk_fma_f32 v[90:91], v[84:85], v[90:91], s[24:25] op_sel_hi:[1,1,0]
	v_add_f32_e32 v59, 1.0, v59
	v_pk_fma_f32 v[90:91], v[84:85], v[90:91], s[26:27] op_sel_hi:[1,1,0]
	v_rcp_f32_e32 v89, v59
	v_pk_mul_f32 v[84:85], v[84:85], v[90:91]
	v_lshlrev_b32_e32 v76, 16, v205
	v_pk_fma_f32 v[84:85], v[86:87], v[84:85], 1.0 op_sel_hi:[1,1,0] neg_lo:[1,0,0] neg_hi:[1,0,0]
	v_and_b32_e32 v77, 0xffff0000, v205
	v_bfi_b32 v83, s17, v85, v83
	v_bfi_b32 v82, s17, v84, v82
	v_pk_add_f32 v[82:83], v[82:83], 1.0 op_sel_hi:[1,0]
	v_pk_add_f32 v[56:57], v[56:57], v[200:201] op_sel_hi:[1,0]
	v_pk_mul_f32 v[78:79], v[78:79], v[82:83]
	s_nop 0
	v_pk_mul_f32 v[54:55], v[54:55], v[78:79]
	v_pk_mul_f32 v[78:79], v[88:89], v[80:81]
	s_nop 0
	v_pk_mul_f32 v[54:55], v[78:79], v[54:55]
	v_pk_mul_f32 v[78:79], v[60:61], s[18:19] op_sel_hi:[1,0]
	v_cvt_pk_bf16_f32 v54, v54, v55
	v_fma_f32 v55, |v78|, s3, 1.0
	v_rcp_f32_e32 v80, v55
	v_mul_f32_e64 v55, |v78|, s16
	v_mul_f32_e64 v55, |v78|, v55
	v_exp_f32_e32 v82, v55
	v_mul_f32_e32 v55, 0xbfb8aa3b, v76
	v_exp_f32_e32 v55, v55
	v_pk_mul_f32 v[60:61], v[60:61], 0.5 op_sel_hi:[1,0]
	v_add_f32_e32 v55, 1.0, v55
	v_rcp_f32_e32 v84, v55
	v_fma_f32 v55, |v79|, s3, 1.0
	v_rcp_f32_e32 v81, v55
	v_mul_f32_e64 v55, |v79|, s16
	v_mul_f32_e64 v55, |v79|, v55
	v_exp_f32_e32 v83, v55
	v_mul_f32_e32 v55, 0xbfb8aa3b, v77
	v_pk_fma_f32 v[86:87], v[80:81], s[20:21], v[62:63] op_sel_hi:[1,0,0]
	v_exp_f32_e32 v55, v55
	v_pk_fma_f32 v[86:87], v[80:81], v[86:87], s[22:23] op_sel_hi:[1,1,0]
	v_add_f32_e32 v55, 1.0, v55
	v_pk_fma_f32 v[86:87], v[80:81], v[86:87], s[24:25] op_sel_hi:[1,1,0]
	v_rcp_f32_e32 v85, v55
	v_pk_fma_f32 v[86:87], v[80:81], v[86:87], s[26:27] op_sel_hi:[1,1,0]
	v_pk_mul_f32 v[58:59], v[84:85], v[76:77]
	v_pk_mul_f32 v[80:81], v[80:81], v[86:87]
	s_nop 0
	v_pk_fma_f32 v[80:81], v[82:83], v[80:81], 1.0 op_sel_hi:[1,1,0] neg_lo:[1,0,0] neg_hi:[1,0,0]
	s_nop 0
	v_bfi_b32 v79, s17, v81, v79
	v_bfi_b32 v78, s17, v80, v78
	v_pk_add_f32 v[78:79], v[78:79], 1.0 op_sel_hi:[1,0]
	s_nop 0
	v_pk_mul_f32 v[60:61], v[60:61], v[78:79]
	s_nop 0
	v_pk_mul_f32 v[56:57], v[56:57], v[60:61]
	s_nop 0
	v_pk_mul_f32 v[56:57], v[58:59], v[56:57]
	s_nop 0
	v_cvt_pk_bf16_f32 v55, v56, v57
	global_store_dwordx2 v[70:71], v[54:55], off offset:1088
	s_nop 0
	s_waitcnt vmcnt(3)
	v_lshlrev_b32_e32 v60, 16, v208
	v_and_b32_e32 v61, 0xffff0000, v208
	v_pk_mul_f32 v[74:75], v[60:61], s[18:19] op_sel_hi:[1,0]
	v_lshlrev_b32_e32 v72, 16, v210
	v_fma_f32 v55, |v74|, s3, 1.0
	v_rcp_f32_e32 v76, v55
	v_mul_f32_e64 v55, |v74|, s16
	v_mul_f32_e64 v55, |v74|, v55
	v_exp_f32_e32 v78, v55
	v_mul_f32_e32 v55, 0xbfb8aa3b, v72
	v_exp_f32_e32 v55, v55
	v_and_b32_e32 v73, 0xffff0000, v210
	v_pk_mul_f32 v[60:61], v[60:61], 0.5 op_sel_hi:[1,0]
	v_lshlrev_b32_e32 v56, 16, v209
	v_add_f32_e32 v55, 1.0, v55
	v_rcp_f32_e32 v80, v55
	v_fma_f32 v55, |v75|, s3, 1.0
	v_rcp_f32_e32 v77, v55
	v_mul_f32_e64 v55, |v75|, s16
	v_mul_f32_e64 v55, |v75|, v55
	v_exp_f32_e32 v79, v55
	v_pk_add_f32 v[50:51], v[50:51], v[206:207] op_sel_hi:[1,0]
	v_mul_f32_e32 v55, 0xbfb8aa3b, v73
	v_pk_fma_f32 v[82:83], v[76:77], s[20:21], v[62:63] op_sel_hi:[1,0,0]
	v_exp_f32_e32 v55, v55
	v_pk_fma_f32 v[82:83], v[76:77], v[82:83], s[22:23] op_sel_hi:[1,1,0]
	v_and_b32_e32 v57, 0xffff0000, v209
	v_pk_fma_f32 v[82:83], v[76:77], v[82:83], s[24:25] op_sel_hi:[1,1,0]
	v_add_f32_e32 v55, 1.0, v55
	v_pk_fma_f32 v[82:83], v[76:77], v[82:83], s[26:27] op_sel_hi:[1,1,0]
	v_rcp_f32_e32 v81, v55
	v_pk_mul_f32 v[76:77], v[76:77], v[82:83]
	v_lshlrev_b32_e32 v58, 16, v211
	v_pk_fma_f32 v[76:77], v[78:79], v[76:77], 1.0 op_sel_hi:[1,1,0] neg_lo:[1,0,0] neg_hi:[1,0,0]
	v_and_b32_e32 v59, 0xffff0000, v211
	v_bfi_b32 v75, s17, v77, v75
	v_bfi_b32 v74, s17, v76, v74
	v_pk_add_f32 v[74:75], v[74:75], 1.0 op_sel_hi:[1,0]
	v_pk_add_f32 v[52:53], v[52:53], v[206:207] op_sel_hi:[1,0]
	v_pk_mul_f32 v[60:61], v[60:61], v[74:75]
	s_nop 0
	v_pk_mul_f32 v[50:51], v[50:51], v[60:61]
	v_pk_mul_f32 v[60:61], v[80:81], v[72:73]
	s_nop 0
	v_pk_mul_f32 v[50:51], v[60:61], v[50:51]
	v_pk_mul_f32 v[60:61], v[56:57], s[18:19] op_sel_hi:[1,0]
	v_cvt_pk_bf16_f32 v50, v50, v51
	v_fma_f32 v51, |v60|, s3, 1.0
	v_rcp_f32_e32 v72, v51
	v_mul_f32_e64 v51, |v60|, s16
	v_mul_f32_e64 v51, |v60|, v51
	v_exp_f32_e32 v74, v51
	v_mul_f32_e32 v51, 0xbfb8aa3b, v58
	v_exp_f32_e32 v51, v51
	v_pk_mul_f32 v[56:57], v[56:57], 0.5 op_sel_hi:[1,0]
	v_add_f32_e32 v51, 1.0, v51
	v_rcp_f32_e32 v76, v51
	v_fma_f32 v51, |v61|, s3, 1.0
	v_rcp_f32_e32 v73, v51
	v_mul_f32_e64 v51, |v61|, s16
	v_mul_f32_e64 v51, |v61|, v51
	v_exp_f32_e32 v75, v51
	v_mul_f32_e32 v51, 0xbfb8aa3b, v59
	v_pk_fma_f32 v[78:79], v[72:73], s[20:21], v[62:63] op_sel_hi:[1,0,0]
	v_exp_f32_e32 v51, v51
	v_pk_fma_f32 v[78:79], v[72:73], v[78:79], s[22:23] op_sel_hi:[1,1,0]
	v_add_f32_e32 v51, 1.0, v51
	v_pk_fma_f32 v[78:79], v[72:73], v[78:79], s[24:25] op_sel_hi:[1,1,0]
	v_rcp_f32_e32 v77, v51
	v_pk_fma_f32 v[78:79], v[72:73], v[78:79], s[26:27] op_sel_hi:[1,1,0]
	v_pk_mul_f32 v[54:55], v[76:77], v[58:59]
	v_pk_mul_f32 v[72:73], v[72:73], v[78:79]
	s_nop 0
	v_pk_fma_f32 v[72:73], v[74:75], v[72:73], 1.0 op_sel_hi:[1,1,0] neg_lo:[1,0,0] neg_hi:[1,0,0]
	s_nop 0
	v_bfi_b32 v61, s17, v73, v61
	v_bfi_b32 v60, s17, v72, v60
	v_pk_add_f32 v[60:61], v[60:61], 1.0 op_sel_hi:[1,0]
	s_nop 0
	v_pk_mul_f32 v[56:57], v[56:57], v[60:61]
	s_nop 0
	v_pk_mul_f32 v[52:53], v[52:53], v[56:57]
	s_nop 0
	v_pk_mul_f32 v[52:53], v[54:55], v[52:53]
	v_or_b32_e32 v54, 16, v66
	v_cvt_pk_bf16_f32 v51, v52, v53
	global_store_dwordx2 v[70:71], v[50:51], off offset:1120
	v_mad_i64_i32 v[50:51], s[0:1], v54, s78, v[68:69]
	v_lshl_add_u64 v[50:51], v[50:51], 0, s[34:35]
	v_lshl_add_u64 v[52:53], v[50:51], 0, v[0:1]
	global_load_dwordx2 v[58:59], v[52:53], off offset:2048
	v_add_co_u32_e32 v50, vcc, s2, v52
	global_load_dword v56, v[64:65], off offset:64
	s_nop 0
	v_addc_co_u32_e32 v51, vcc, 0, v53, vcc
	global_load_dwordx2 v[212:213], v[50:51], off
	global_load_dword v214, v[64:65], off offset:64
	global_load_dwordx2 v[216:217], v[52:53], off offset:2080
	global_load_dwordx2 v[218:219], v[50:51], off offset:32
	global_load_dword v220, v[64:65], off offset:64
	global_load_dwordx2 v[222:223], v[52:53], off offset:2112
	global_load_dwordx2 v[224:225], v[50:51], off offset:64
	global_load_dword v226, v[64:65], off offset:64
	global_load_dwordx2 v[228:229], v[52:53], off offset:2144
	global_load_dwordx2 v[230:231], v[50:51], off offset:96
	v_ashrrev_i32_e32 v55, 31, v54
	s_waitcnt vmcnt(9)
	v_lshlrev_b32_e32 v70, 16, v58
	v_and_b32_e32 v71, 0xffff0000, v58
	v_pk_mul_f32 v[74:75], v[70:71], s[18:19] op_sel_hi:[1,0]
	v_pk_mul_f32 v[70:71], v[70:71], 0.5 op_sel_hi:[1,0]
	v_fma_f32 v57, |v74|, s3, 1.0
	v_rcp_f32_e32 v76, v57
	v_mul_f32_e64 v57, |v74|, s16
	v_lshlrev_b32_e32 v72, 16, v212
	v_mul_f32_e64 v57, |v74|, v57
	v_exp_f32_e32 v78, v57
	v_mul_f32_e32 v57, 0xbfb8aa3b, v72
	v_exp_f32_e32 v57, v57
	v_and_b32_e32 v73, 0xffff0000, v212
	v_lshlrev_b32_e32 v60, 16, v213
	v_and_b32_e32 v61, 0xffff0000, v213
	v_add_f32_e32 v57, 1.0, v57
	v_rcp_f32_e32 v80, v57
	v_fma_f32 v57, |v75|, s3, 1.0
	v_rcp_f32_e32 v77, v57
	v_mul_f32_e64 v57, |v75|, s16
	v_mul_f32_e64 v57, |v75|, v57
	v_exp_f32_e32 v79, v57
	v_pk_add_f32 v[46:47], v[46:47], v[56:57] op_sel_hi:[1,0]
	v_mul_f32_e32 v57, 0xbfb8aa3b, v73
	v_pk_fma_f32 v[82:83], v[76:77], s[20:21], v[62:63] op_sel_hi:[1,0,0]
	v_exp_f32_e32 v57, v57
	v_pk_fma_f32 v[82:83], v[76:77], v[82:83], s[22:23] op_sel_hi:[1,1,0]
	v_add_f32_e32 v57, 1.0, v57
	v_pk_fma_f32 v[82:83], v[76:77], v[82:83], s[24:25] op_sel_hi:[1,1,0]
	v_rcp_f32_e32 v81, v57
	v_pk_fma_f32 v[82:83], v[76:77], v[82:83], s[26:27] op_sel_hi:[1,1,0]
	s_nop 0
	v_pk_mul_f32 v[76:77], v[76:77], v[82:83]
	s_nop 0
	v_pk_fma_f32 v[76:77], v[78:79], v[76:77], 1.0 op_sel_hi:[1,1,0] neg_lo:[1,0,0] neg_hi:[1,0,0]
	s_nop 0
	v_bfi_b32 v75, s17, v77, v75
	v_bfi_b32 v74, s17, v76, v74
	v_pk_add_f32 v[74:75], v[74:75], 1.0 op_sel_hi:[1,0]
	s_nop 0
	v_pk_mul_f32 v[70:71], v[70:71], v[74:75]
	s_nop 0
	v_pk_mul_f32 v[46:47], v[46:47], v[70:71]
	v_pk_mul_f32 v[70:71], v[80:81], v[72:73]
	s_nop 0
	v_pk_mul_f32 v[46:47], v[70:71], v[46:47]
	s_nop 0
	v_cvt_pk_bf16_f32 v58, v46, v47
	v_lshlrev_b32_e32 v46, 16, v59
	v_and_b32_e32 v47, 0xffff0000, v59
	v_pk_mul_f32 v[70:71], v[46:47], s[18:19] op_sel_hi:[1,0]
	v_pk_mul_f32 v[46:47], v[46:47], 0.5 op_sel_hi:[1,0]
	v_fma_f32 v57, |v70|, s3, 1.0
	v_rcp_f32_e32 v72, v57
	v_mul_f32_e64 v57, |v70|, s16
	v_mul_f32_e64 v57, |v70|, v57
	v_exp_f32_e32 v74, v57
	v_mul_f32_e32 v57, 0xbfb8aa3b, v60
	v_exp_f32_e32 v57, v57
	s_nop 0
	v_add_f32_e32 v57, 1.0, v57
	v_rcp_f32_e32 v76, v57
	v_fma_f32 v57, |v71|, s3, 1.0
	v_rcp_f32_e32 v73, v57
	v_mul_f32_e64 v57, |v71|, s16
	v_mul_f32_e64 v57, |v71|, v57
	v_exp_f32_e32 v75, v57
	v_pk_fma_f32 v[78:79], v[72:73], s[20:21], v[62:63] op_sel_hi:[1,0,0]
	v_pk_add_f32 v[48:49], v[48:49], v[56:57] op_sel_hi:[1,0]
	v_pk_fma_f32 v[78:79], v[72:73], v[78:79], s[22:23] op_sel_hi:[1,1,0]
	s_nop 0
	v_pk_fma_f32 v[78:79], v[72:73], v[78:79], s[24:25] op_sel_hi:[1,1,0]
	s_nop 0
	v_pk_fma_f32 v[78:79], v[72:73], v[78:79], s[26:27] op_sel_hi:[1,1,0]
	s_nop 0
	v_pk_mul_f32 v[72:73], v[72:73], v[78:79]
	s_nop 0
	v_pk_fma_f32 v[72:73], v[74:75], v[72:73], 1.0 op_sel_hi:[1,1,0] neg_lo:[1,0,0] neg_hi:[1,0,0]
	s_nop 0
	v_bfi_b32 v71, s17, v73, v71
	v_bfi_b32 v70, s17, v72, v70
	v_pk_add_f32 v[70:71], v[70:71], 1.0 op_sel_hi:[1,0]
	s_nop 0
	v_pk_mul_f32 v[46:47], v[46:47], v[70:71]
	s_nop 0
	v_pk_mul_f32 v[46:47], v[48:49], v[46:47]
	v_mul_f32_e32 v48, 0xbfb8aa3b, v61
	v_exp_f32_e32 v48, v48
	s_nop 0
	v_add_f32_e32 v48, 1.0, v48
	v_rcp_f32_e32 v77, v48
	s_nop 0
	v_pk_mul_f32 v[48:49], v[76:77], v[60:61]
	s_nop 0
	v_pk_mul_f32 v[46:47], v[48:49], v[46:47]
	s_nop 0
	v_cvt_pk_bf16_f32 v59, v46, v47
	v_lshlrev_b64 v[46:47], 11, v[54:55]
	v_lshl_add_u64 v[46:47], s[60:61], 0, v[46:47]
	v_lshl_add_u64 v[46:47], v[46:47], 0, s[34:35]
	v_lshl_add_u64 v[46:47], v[46:47], 0, v[0:1]
	global_store_dwordx2 v[46:47], v[58:59], off offset:1024
	s_waitcnt vmcnt(7)
	v_lshlrev_b32_e32 v58, 16, v216
	v_and_b32_e32 v59, 0xffff0000, v216
	v_pk_mul_f32 v[70:71], v[58:59], s[18:19] op_sel_hi:[1,0]
	v_lshlrev_b32_e32 v60, 16, v218
	v_fma_f32 v49, |v70|, s3, 1.0
	v_rcp_f32_e32 v72, v49
	v_mul_f32_e64 v49, |v70|, s16
	v_mul_f32_e64 v49, |v70|, v49
	v_exp_f32_e32 v74, v49
	v_mul_f32_e32 v49, 0xbfb8aa3b, v60
	v_exp_f32_e32 v49, v49
	v_and_b32_e32 v61, 0xffff0000, v218
	v_pk_mul_f32 v[58:59], v[58:59], 0.5 op_sel_hi:[1,0]
	v_lshlrev_b32_e32 v54, 16, v217
	v_add_f32_e32 v49, 1.0, v49
	v_rcp_f32_e32 v76, v49
	v_fma_f32 v49, |v71|, s3, 1.0
	v_rcp_f32_e32 v73, v49
	v_mul_f32_e64 v49, |v71|, s16
	v_mul_f32_e64 v49, |v71|, v49
	v_exp_f32_e32 v75, v49
	v_pk_add_f32 v[42:43], v[42:43], v[214:215] op_sel_hi:[1,0]
	v_mul_f32_e32 v49, 0xbfb8aa3b, v61
	v_pk_fma_f32 v[78:79], v[72:73], s[20:21], v[62:63] op_sel_hi:[1,0,0]
	v_exp_f32_e32 v49, v49
	v_pk_fma_f32 v[78:79], v[72:73], v[78:79], s[22:23] op_sel_hi:[1,1,0]
	v_and_b32_e32 v55, 0xffff0000, v217
	v_pk_fma_f32 v[78:79], v[72:73], v[78:79], s[24:25] op_sel_hi:[1,1,0]
	v_add_f32_e32 v49, 1.0, v49
	v_pk_fma_f32 v[78:79], v[72:73], v[78:79], s[26:27] op_sel_hi:[1,1,0]
	v_rcp_f32_e32 v77, v49
	v_pk_mul_f32 v[72:73], v[72:73], v[78:79]
	v_lshlrev_b32_e32 v56, 16, v219
	v_pk_fma_f32 v[72:73], v[74:75], v[72:73], 1.0 op_sel_hi:[1,1,0] neg_lo:[1,0,0] neg_hi:[1,0,0]
	v_and_b32_e32 v57, 0xffff0000, v219
	v_bfi_b32 v71, s17, v73, v71
	v_bfi_b32 v70, s17, v72, v70
	v_pk_add_f32 v[70:71], v[70:71], 1.0 op_sel_hi:[1,0]
	v_pk_add_f32 v[44:45], v[44:45], v[214:215] op_sel_hi:[1,0]
	v_pk_mul_f32 v[58:59], v[58:59], v[70:71]
	s_nop 0
	v_pk_mul_f32 v[42:43], v[42:43], v[58:59]
	v_pk_mul_f32 v[58:59], v[76:77], v[60:61]
	s_nop 0
	v_pk_mul_f32 v[42:43], v[58:59], v[42:43]
	v_pk_mul_f32 v[58:59], v[54:55], s[18:19] op_sel_hi:[1,0]
	v_cvt_pk_bf16_f32 v42, v42, v43
	v_fma_f32 v43, |v58|, s3, 1.0
	v_rcp_f32_e32 v60, v43
	v_mul_f32_e64 v43, |v58|, s16
	v_mul_f32_e64 v43, |v58|, v43
	v_exp_f32_e32 v70, v43
	v_mul_f32_e32 v43, 0xbfb8aa3b, v56
	v_exp_f32_e32 v43, v43
	v_pk_mul_f32 v[54:55], v[54:55], 0.5 op_sel_hi:[1,0]
	v_add_f32_e32 v43, 1.0, v43
	v_rcp_f32_e32 v72, v43
	v_fma_f32 v43, |v59|, s3, 1.0
	v_rcp_f32_e32 v61, v43
	v_mul_f32_e64 v43, |v59|, s16
	v_mul_f32_e64 v43, |v59|, v43
	v_exp_f32_e32 v71, v43
	v_mul_f32_e32 v43, 0xbfb8aa3b, v57
	v_pk_fma_f32 v[74:75], v[60:61], s[20:21], v[62:63] op_sel_hi:[1,0,0]
	v_exp_f32_e32 v43, v43
	v_pk_fma_f32 v[74:75], v[60:61], v[74:75], s[22:23] op_sel_hi:[1,1,0]
	v_add_f32_e32 v43, 1.0, v43
	v_pk_fma_f32 v[74:75], v[60:61], v[74:75], s[24:25] op_sel_hi:[1,1,0]
	v_rcp_f32_e32 v73, v43
	v_pk_fma_f32 v[74:75], v[60:61], v[74:75], s[26:27] op_sel_hi:[1,1,0]
	v_pk_mul_f32 v[48:49], v[72:73], v[56:57]
	v_pk_mul_f32 v[60:61], v[60:61], v[74:75]
	s_nop 0
	v_pk_fma_f32 v[60:61], v[70:71], v[60:61], 1.0 op_sel_hi:[1,1,0] neg_lo:[1,0,0] neg_hi:[1,0,0]
	s_nop 0
	v_bfi_b32 v59, s17, v61, v59
	v_bfi_b32 v58, s17, v60, v58
	v_pk_add_f32 v[58:59], v[58:59], 1.0 op_sel_hi:[1,0]
	s_nop 0
	v_pk_mul_f32 v[54:55], v[54:55], v[58:59]
	s_nop 0
	v_pk_mul_f32 v[44:45], v[44:45], v[54:55]
	s_nop 0
	v_pk_mul_f32 v[44:45], v[48:49], v[44:45]
	s_nop 0
	v_cvt_pk_bf16_f32 v43, v44, v45
	global_store_dwordx2 v[46:47], v[42:43], off offset:1056
	s_nop 0
	s_waitcnt vmcnt(5)
	v_lshlrev_b32_e32 v54, 16, v222
	v_and_b32_e32 v55, 0xffff0000, v222
	v_pk_mul_f32 v[58:59], v[54:55], s[18:19] op_sel_hi:[1,0]
	v_lshlrev_b32_e32 v56, 16, v224
	v_fma_f32 v43, |v58|, s3, 1.0
	v_rcp_f32_e32 v60, v43
	v_mul_f32_e64 v43, |v58|, s16
	v_mul_f32_e64 v43, |v58|, v43
	v_exp_f32_e32 v70, v43
	v_mul_f32_e32 v43, 0xbfb8aa3b, v56
	v_exp_f32_e32 v43, v43
	v_and_b32_e32 v57, 0xffff0000, v224
	v_pk_mul_f32 v[54:55], v[54:55], 0.5 op_sel_hi:[1,0]
	v_lshlrev_b32_e32 v44, 16, v223
	v_add_f32_e32 v43, 1.0, v43
	v_rcp_f32_e32 v72, v43
	v_fma_f32 v43, |v59|, s3, 1.0
	v_rcp_f32_e32 v61, v43
	v_mul_f32_e64 v43, |v59|, s16
	v_mul_f32_e64 v43, |v59|, v43
	v_exp_f32_e32 v71, v43
	v_pk_add_f32 v[38:39], v[38:39], v[220:221] op_sel_hi:[1,0]
	v_mul_f32_e32 v43, 0xbfb8aa3b, v57
	v_pk_fma_f32 v[74:75], v[60:61], s[20:21], v[62:63] op_sel_hi:[1,0,0]
	v_exp_f32_e32 v43, v43
	v_pk_fma_f32 v[74:75], v[60:61], v[74:75], s[22:23] op_sel_hi:[1,1,0]
	v_and_b32_e32 v45, 0xffff0000, v223
	v_pk_fma_f32 v[74:75], v[60:61], v[74:75], s[24:25] op_sel_hi:[1,1,0]
	v_add_f32_e32 v43, 1.0, v43
	v_pk_fma_f32 v[74:75], v[60:61], v[74:75], s[26:27] op_sel_hi:[1,1,0]
	v_rcp_f32_e32 v73, v43
	v_pk_mul_f32 v[60:61], v[60:61], v[74:75]
	v_lshlrev_b32_e32 v48, 16, v225
	v_pk_fma_f32 v[60:61], v[70:71], v[60:61], 1.0 op_sel_hi:[1,1,0] neg_lo:[1,0,0] neg_hi:[1,0,0]
	v_and_b32_e32 v49, 0xffff0000, v225
	v_bfi_b32 v59, s17, v61, v59
	v_bfi_b32 v58, s17, v60, v58
	v_pk_add_f32 v[58:59], v[58:59], 1.0 op_sel_hi:[1,0]
	v_pk_add_f32 v[40:41], v[40:41], v[220:221] op_sel_hi:[1,0]
	v_pk_mul_f32 v[54:55], v[54:55], v[58:59]
	s_nop 0
	v_pk_mul_f32 v[38:39], v[38:39], v[54:55]
	v_pk_mul_f32 v[54:55], v[72:73], v[56:57]
	s_nop 0
	v_pk_mul_f32 v[38:39], v[54:55], v[38:39]
	v_pk_mul_f32 v[54:55], v[44:45], s[18:19] op_sel_hi:[1,0]
	v_cvt_pk_bf16_f32 v38, v38, v39
	v_fma_f32 v39, |v54|, s3, 1.0
	v_rcp_f32_e32 v56, v39
	v_mul_f32_e64 v39, |v54|, s16
	v_mul_f32_e64 v39, |v54|, v39
	v_exp_f32_e32 v58, v39
	v_mul_f32_e32 v39, 0xbfb8aa3b, v48
	v_exp_f32_e32 v39, v39
	v_pk_mul_f32 v[44:45], v[44:45], 0.5 op_sel_hi:[1,0]
	v_add_f32_e32 v39, 1.0, v39
	v_rcp_f32_e32 v60, v39
	v_fma_f32 v39, |v55|, s3, 1.0
	v_rcp_f32_e32 v57, v39
	v_mul_f32_e64 v39, |v55|, s16
	v_mul_f32_e64 v39, |v55|, v39
	v_exp_f32_e32 v59, v39
	v_mul_f32_e32 v39, 0xbfb8aa3b, v49
	v_pk_fma_f32 v[70:71], v[56:57], s[20:21], v[62:63] op_sel_hi:[1,0,0]
	v_exp_f32_e32 v39, v39
	v_pk_fma_f32 v[70:71], v[56:57], v[70:71], s[22:23] op_sel_hi:[1,1,0]
	v_add_f32_e32 v39, 1.0, v39
	v_pk_fma_f32 v[70:71], v[56:57], v[70:71], s[24:25] op_sel_hi:[1,1,0]
	v_rcp_f32_e32 v61, v39
	v_pk_fma_f32 v[70:71], v[56:57], v[70:71], s[26:27] op_sel_hi:[1,1,0]
	v_pk_mul_f32 v[42:43], v[60:61], v[48:49]
	v_pk_mul_f32 v[56:57], v[56:57], v[70:71]
	s_nop 0
	v_pk_fma_f32 v[56:57], v[58:59], v[56:57], 1.0 op_sel_hi:[1,1,0] neg_lo:[1,0,0] neg_hi:[1,0,0]
	s_nop 0
	v_bfi_b32 v55, s17, v57, v55
	v_bfi_b32 v54, s17, v56, v54
	v_pk_add_f32 v[54:55], v[54:55], 1.0 op_sel_hi:[1,0]
	s_nop 0
	v_pk_mul_f32 v[44:45], v[44:45], v[54:55]
	s_nop 0
	v_pk_mul_f32 v[40:41], v[40:41], v[44:45]
	s_nop 0
	v_pk_mul_f32 v[40:41], v[42:43], v[40:41]
	s_nop 0
	v_cvt_pk_bf16_f32 v39, v40, v41
	global_store_dwordx2 v[46:47], v[38:39], off offset:1088
	s_nop 0
	s_waitcnt vmcnt(3)
	v_lshlrev_b32_e32 v44, 16, v228
	v_and_b32_e32 v45, 0xffff0000, v228
	v_pk_mul_f32 v[50:51], v[44:45], s[18:19] op_sel_hi:[1,0]
	v_lshlrev_b32_e32 v48, 16, v230
	v_fma_f32 v39, |v50|, s3, 1.0
	v_rcp_f32_e32 v52, v39
	v_mul_f32_e64 v39, |v50|, s16
	v_mul_f32_e64 v39, |v50|, v39
	v_exp_f32_e32 v54, v39
	v_mul_f32_e32 v39, 0xbfb8aa3b, v48
	v_exp_f32_e32 v39, v39
	v_and_b32_e32 v49, 0xffff0000, v230
	v_pk_mul_f32 v[44:45], v[44:45], 0.5 op_sel_hi:[1,0]
	v_lshlrev_b32_e32 v40, 16, v229
	v_add_f32_e32 v39, 1.0, v39
	v_rcp_f32_e32 v56, v39
	v_fma_f32 v39, |v51|, s3, 1.0
	v_rcp_f32_e32 v53, v39
	v_mul_f32_e64 v39, |v51|, s16
	v_mul_f32_e64 v39, |v51|, v39
	v_exp_f32_e32 v55, v39
	v_pk_add_f32 v[34:35], v[34:35], v[226:227] op_sel_hi:[1,0]
	v_mul_f32_e32 v39, 0xbfb8aa3b, v49
	v_pk_fma_f32 v[58:59], v[52:53], s[20:21], v[62:63] op_sel_hi:[1,0,0]
	v_exp_f32_e32 v39, v39
	v_pk_fma_f32 v[58:59], v[52:53], v[58:59], s[22:23] op_sel_hi:[1,1,0]
	v_and_b32_e32 v41, 0xffff0000, v229
	v_pk_fma_f32 v[58:59], v[52:53], v[58:59], s[24:25] op_sel_hi:[1,1,0]
	v_add_f32_e32 v39, 1.0, v39
	v_pk_fma_f32 v[58:59], v[52:53], v[58:59], s[26:27] op_sel_hi:[1,1,0]
	v_rcp_f32_e32 v57, v39
	v_pk_mul_f32 v[52:53], v[52:53], v[58:59]
	v_lshlrev_b32_e32 v42, 16, v231
	v_pk_fma_f32 v[52:53], v[54:55], v[52:53], 1.0 op_sel_hi:[1,1,0] neg_lo:[1,0,0] neg_hi:[1,0,0]
	v_and_b32_e32 v43, 0xffff0000, v231
	v_bfi_b32 v51, s17, v53, v51
	v_bfi_b32 v50, s17, v52, v50
	v_pk_add_f32 v[50:51], v[50:51], 1.0 op_sel_hi:[1,0]
	v_pk_add_f32 v[36:37], v[36:37], v[226:227] op_sel_hi:[1,0]
	v_pk_mul_f32 v[44:45], v[44:45], v[50:51]
	s_nop 0
	v_pk_mul_f32 v[34:35], v[34:35], v[44:45]
	v_pk_mul_f32 v[44:45], v[56:57], v[48:49]
	s_nop 0
	v_pk_mul_f32 v[34:35], v[44:45], v[34:35]
	v_pk_mul_f32 v[44:45], v[40:41], s[18:19] op_sel_hi:[1,0]
	v_cvt_pk_bf16_f32 v34, v34, v35
	v_fma_f32 v35, |v44|, s3, 1.0
	v_rcp_f32_e32 v48, v35
	v_mul_f32_e64 v35, |v44|, s16
	v_mul_f32_e64 v35, |v44|, v35
	v_exp_f32_e32 v50, v35
	v_mul_f32_e32 v35, 0xbfb8aa3b, v42
	v_exp_f32_e32 v35, v35
	v_pk_mul_f32 v[40:41], v[40:41], 0.5 op_sel_hi:[1,0]
	v_add_f32_e32 v35, 1.0, v35
	v_rcp_f32_e32 v52, v35
	v_fma_f32 v35, |v45|, s3, 1.0
	v_rcp_f32_e32 v49, v35
	v_mul_f32_e64 v35, |v45|, s16
	v_mul_f32_e64 v35, |v45|, v35
	v_exp_f32_e32 v51, v35
	v_mul_f32_e32 v35, 0xbfb8aa3b, v43
	v_pk_fma_f32 v[54:55], v[48:49], s[20:21], v[62:63] op_sel_hi:[1,0,0]
	v_exp_f32_e32 v35, v35
	v_pk_fma_f32 v[54:55], v[48:49], v[54:55], s[22:23] op_sel_hi:[1,1,0]
	v_add_f32_e32 v35, 1.0, v35
	v_pk_fma_f32 v[54:55], v[48:49], v[54:55], s[24:25] op_sel_hi:[1,1,0]
	v_rcp_f32_e32 v53, v35
	v_pk_fma_f32 v[54:55], v[48:49], v[54:55], s[26:27] op_sel_hi:[1,1,0]
	v_pk_mul_f32 v[38:39], v[52:53], v[42:43]
	v_pk_mul_f32 v[48:49], v[48:49], v[54:55]
	s_nop 0
	v_pk_fma_f32 v[48:49], v[50:51], v[48:49], 1.0 op_sel_hi:[1,1,0] neg_lo:[1,0,0] neg_hi:[1,0,0]
	s_nop 0
	v_bfi_b32 v45, s17, v49, v45
	v_bfi_b32 v44, s17, v48, v44
	v_pk_add_f32 v[44:45], v[44:45], 1.0 op_sel_hi:[1,0]
	s_nop 0
	v_pk_mul_f32 v[40:41], v[40:41], v[44:45]
	s_nop 0
	v_pk_mul_f32 v[36:37], v[36:37], v[40:41]
	s_nop 0
	v_pk_mul_f32 v[36:37], v[38:39], v[36:37]
	v_or_b32_e32 v38, 32, v66
	v_cvt_pk_bf16_f32 v35, v36, v37
	global_store_dwordx2 v[46:47], v[34:35], off offset:1120
	v_mad_i64_i32 v[34:35], s[0:1], v38, s78, v[68:69]
	v_lshl_add_u64 v[34:35], v[34:35], 0, s[34:35]
	v_lshl_add_u64 v[36:37], v[34:35], 0, v[0:1]
	global_load_dwordx2 v[42:43], v[36:37], off offset:2048
	v_add_co_u32_e32 v34, vcc, s2, v36
	global_load_dword v40, v[64:65], off offset:128
	s_nop 0
	v_addc_co_u32_e32 v35, vcc, 0, v37, vcc
	global_load_dwordx2 v[232:233], v[34:35], off
	global_load_dword v234, v[64:65], off offset:128
	global_load_dwordx2 v[236:237], v[36:37], off offset:2080
	global_load_dwordx2 v[238:239], v[34:35], off offset:32
	global_load_dword v240, v[64:65], off offset:128
	global_load_dwordx2 v[242:243], v[36:37], off offset:2112
	global_load_dwordx2 v[244:245], v[34:35], off offset:64
	global_load_dword v246, v[64:65], off offset:128
	global_load_dwordx2 v[248:249], v[36:37], off offset:2144
	global_load_dwordx2 v[250:251], v[34:35], off offset:96
	v_ashrrev_i32_e32 v39, 31, v38
	s_waitcnt vmcnt(9)
	v_lshlrev_b32_e32 v46, 16, v42
	v_and_b32_e32 v47, 0xffff0000, v42
	v_pk_mul_f32 v[50:51], v[46:47], s[18:19] op_sel_hi:[1,0]
	v_pk_mul_f32 v[46:47], v[46:47], 0.5 op_sel_hi:[1,0]
	v_fma_f32 v41, |v50|, s3, 1.0
	v_rcp_f32_e32 v52, v41
	v_mul_f32_e64 v41, |v50|, s16
	v_lshlrev_b32_e32 v48, 16, v232
	v_mul_f32_e64 v41, |v50|, v41
	v_exp_f32_e32 v54, v41
	v_mul_f32_e32 v41, 0xbfb8aa3b, v48
	v_exp_f32_e32 v41, v41
	v_and_b32_e32 v49, 0xffff0000, v232
	v_lshlrev_b32_e32 v44, 16, v233
	v_and_b32_e32 v45, 0xffff0000, v233
	v_add_f32_e32 v41, 1.0, v41
	v_rcp_f32_e32 v56, v41
	v_fma_f32 v41, |v51|, s3, 1.0
	v_rcp_f32_e32 v53, v41
	v_mul_f32_e64 v41, |v51|, s16
	v_mul_f32_e64 v41, |v51|, v41
	v_exp_f32_e32 v55, v41
	v_pk_add_f32 v[30:31], v[30:31], v[40:41] op_sel_hi:[1,0]
	v_mul_f32_e32 v41, 0xbfb8aa3b, v49
	v_pk_fma_f32 v[58:59], v[52:53], s[20:21], v[62:63] op_sel_hi:[1,0,0]
	v_exp_f32_e32 v41, v41
	v_pk_fma_f32 v[58:59], v[52:53], v[58:59], s[22:23] op_sel_hi:[1,1,0]
	v_add_f32_e32 v41, 1.0, v41
	v_pk_fma_f32 v[58:59], v[52:53], v[58:59], s[24:25] op_sel_hi:[1,1,0]
	v_rcp_f32_e32 v57, v41
	v_pk_fma_f32 v[58:59], v[52:53], v[58:59], s[26:27] op_sel_hi:[1,1,0]
	s_nop 0
	v_pk_mul_f32 v[52:53], v[52:53], v[58:59]
	s_nop 0
	v_pk_fma_f32 v[52:53], v[54:55], v[52:53], 1.0 op_sel_hi:[1,1,0] neg_lo:[1,0,0] neg_hi:[1,0,0]
	s_nop 0
	v_bfi_b32 v51, s17, v53, v51
	v_bfi_b32 v50, s17, v52, v50
	v_pk_add_f32 v[50:51], v[50:51], 1.0 op_sel_hi:[1,0]
	s_nop 0
	v_pk_mul_f32 v[46:47], v[46:47], v[50:51]
	s_nop 0
	v_pk_mul_f32 v[30:31], v[30:31], v[46:47]
	v_pk_mul_f32 v[46:47], v[56:57], v[48:49]
	s_nop 0
	v_pk_mul_f32 v[30:31], v[46:47], v[30:31]
	s_nop 0
	v_cvt_pk_bf16_f32 v42, v30, v31
	v_lshlrev_b32_e32 v30, 16, v43
	v_and_b32_e32 v31, 0xffff0000, v43
	v_pk_mul_f32 v[46:47], v[30:31], s[18:19] op_sel_hi:[1,0]
	v_pk_mul_f32 v[30:31], v[30:31], 0.5 op_sel_hi:[1,0]
	v_fma_f32 v41, |v46|, s3, 1.0
	v_rcp_f32_e32 v48, v41
	v_mul_f32_e64 v41, |v46|, s16
	v_mul_f32_e64 v41, |v46|, v41
	v_exp_f32_e32 v50, v41
	v_mul_f32_e32 v41, 0xbfb8aa3b, v44
	v_exp_f32_e32 v41, v41
	s_nop 0
	v_add_f32_e32 v41, 1.0, v41
	v_rcp_f32_e32 v52, v41
	v_fma_f32 v41, |v47|, s3, 1.0
	v_rcp_f32_e32 v49, v41
	v_mul_f32_e64 v41, |v47|, s16
	v_mul_f32_e64 v41, |v47|, v41
	v_exp_f32_e32 v51, v41
	v_pk_fma_f32 v[54:55], v[48:49], s[20:21], v[62:63] op_sel_hi:[1,0,0]
	v_pk_add_f32 v[32:33], v[32:33], v[40:41] op_sel_hi:[1,0]
	v_pk_fma_f32 v[54:55], v[48:49], v[54:55], s[22:23] op_sel_hi:[1,1,0]
	s_nop 0
	v_pk_fma_f32 v[54:55], v[48:49], v[54:55], s[24:25] op_sel_hi:[1,1,0]
	s_nop 0
	v_pk_fma_f32 v[54:55], v[48:49], v[54:55], s[26:27] op_sel_hi:[1,1,0]
	s_nop 0
	v_pk_mul_f32 v[48:49], v[48:49], v[54:55]
	s_nop 0
	v_pk_fma_f32 v[48:49], v[50:51], v[48:49], 1.0 op_sel_hi:[1,1,0] neg_lo:[1,0,0] neg_hi:[1,0,0]
	s_nop 0
	v_bfi_b32 v47, s17, v49, v47
	v_bfi_b32 v46, s17, v48, v46
	v_pk_add_f32 v[46:47], v[46:47], 1.0 op_sel_hi:[1,0]
	s_nop 0
	v_pk_mul_f32 v[30:31], v[30:31], v[46:47]
	s_nop 0
	v_pk_mul_f32 v[30:31], v[32:33], v[30:31]
	v_mul_f32_e32 v32, 0xbfb8aa3b, v45
	v_exp_f32_e32 v32, v32
	s_nop 0
	v_add_f32_e32 v32, 1.0, v32
	v_rcp_f32_e32 v53, v32
	s_nop 0
	v_pk_mul_f32 v[32:33], v[52:53], v[44:45]
	s_nop 0
	v_pk_mul_f32 v[30:31], v[32:33], v[30:31]
	s_nop 0
	v_cvt_pk_bf16_f32 v43, v30, v31
	v_lshlrev_b64 v[30:31], 11, v[38:39]
	v_lshl_add_u64 v[30:31], s[60:61], 0, v[30:31]
	v_lshl_add_u64 v[30:31], v[30:31], 0, s[34:35]
	v_lshl_add_u64 v[30:31], v[30:31], 0, v[0:1]
	global_store_dwordx2 v[30:31], v[42:43], off offset:1024
	s_waitcnt vmcnt(7)
	v_lshlrev_b32_e32 v42, 16, v236
	v_and_b32_e32 v43, 0xffff0000, v236
	v_pk_mul_f32 v[46:47], v[42:43], s[18:19] op_sel_hi:[1,0]
	v_lshlrev_b32_e32 v44, 16, v238
	v_fma_f32 v33, |v46|, s3, 1.0
	v_rcp_f32_e32 v48, v33
	v_mul_f32_e64 v33, |v46|, s16
	v_mul_f32_e64 v33, |v46|, v33
	v_exp_f32_e32 v50, v33
	v_mul_f32_e32 v33, 0xbfb8aa3b, v44
	v_exp_f32_e32 v33, v33
	v_and_b32_e32 v45, 0xffff0000, v238
	v_pk_mul_f32 v[42:43], v[42:43], 0.5 op_sel_hi:[1,0]
	v_lshlrev_b32_e32 v38, 16, v237
	v_add_f32_e32 v33, 1.0, v33
	v_rcp_f32_e32 v52, v33
	v_fma_f32 v33, |v47|, s3, 1.0
	v_rcp_f32_e32 v49, v33
	v_mul_f32_e64 v33, |v47|, s16
	v_mul_f32_e64 v33, |v47|, v33
	v_exp_f32_e32 v51, v33
	v_pk_add_f32 v[26:27], v[26:27], v[234:235] op_sel_hi:[1,0]
	v_mul_f32_e32 v33, 0xbfb8aa3b, v45
	v_pk_fma_f32 v[54:55], v[48:49], s[20:21], v[62:63] op_sel_hi:[1,0,0]
	v_exp_f32_e32 v33, v33
	v_pk_fma_f32 v[54:55], v[48:49], v[54:55], s[22:23] op_sel_hi:[1,1,0]
	v_and_b32_e32 v39, 0xffff0000, v237
	v_pk_fma_f32 v[54:55], v[48:49], v[54:55], s[24:25] op_sel_hi:[1,1,0]
	v_add_f32_e32 v33, 1.0, v33
	v_pk_fma_f32 v[54:55], v[48:49], v[54:55], s[26:27] op_sel_hi:[1,1,0]
	v_rcp_f32_e32 v53, v33
	v_pk_mul_f32 v[48:49], v[48:49], v[54:55]
	v_lshlrev_b32_e32 v40, 16, v239
	v_pk_fma_f32 v[48:49], v[50:51], v[48:49], 1.0 op_sel_hi:[1,1,0] neg_lo:[1,0,0] neg_hi:[1,0,0]
	v_and_b32_e32 v41, 0xffff0000, v239
	v_bfi_b32 v47, s17, v49, v47
	v_bfi_b32 v46, s17, v48, v46
	v_pk_add_f32 v[46:47], v[46:47], 1.0 op_sel_hi:[1,0]
	v_pk_add_f32 v[28:29], v[28:29], v[234:235] op_sel_hi:[1,0]
	v_pk_mul_f32 v[42:43], v[42:43], v[46:47]
	s_nop 0
	v_pk_mul_f32 v[26:27], v[26:27], v[42:43]
	v_pk_mul_f32 v[42:43], v[52:53], v[44:45]
	s_nop 0
	v_pk_mul_f32 v[26:27], v[42:43], v[26:27]
	v_pk_mul_f32 v[42:43], v[38:39], s[18:19] op_sel_hi:[1,0]
	v_cvt_pk_bf16_f32 v26, v26, v27
	v_fma_f32 v27, |v42|, s3, 1.0
	v_rcp_f32_e32 v44, v27
	v_mul_f32_e64 v27, |v42|, s16
	v_mul_f32_e64 v27, |v42|, v27
	v_exp_f32_e32 v46, v27
	v_mul_f32_e32 v27, 0xbfb8aa3b, v40
	v_exp_f32_e32 v27, v27
	v_pk_mul_f32 v[38:39], v[38:39], 0.5 op_sel_hi:[1,0]
	v_add_f32_e32 v27, 1.0, v27
	v_rcp_f32_e32 v48, v27
	v_fma_f32 v27, |v43|, s3, 1.0
	v_rcp_f32_e32 v45, v27
	v_mul_f32_e64 v27, |v43|, s16
	v_mul_f32_e64 v27, |v43|, v27
	v_exp_f32_e32 v47, v27
	v_mul_f32_e32 v27, 0xbfb8aa3b, v41
	v_pk_fma_f32 v[50:51], v[44:45], s[20:21], v[62:63] op_sel_hi:[1,0,0]
	v_exp_f32_e32 v27, v27
	v_pk_fma_f32 v[50:51], v[44:45], v[50:51], s[22:23] op_sel_hi:[1,1,0]
	v_add_f32_e32 v27, 1.0, v27
	v_pk_fma_f32 v[50:51], v[44:45], v[50:51], s[24:25] op_sel_hi:[1,1,0]
	v_rcp_f32_e32 v49, v27
	v_pk_fma_f32 v[50:51], v[44:45], v[50:51], s[26:27] op_sel_hi:[1,1,0]
	v_pk_mul_f32 v[32:33], v[48:49], v[40:41]
	v_pk_mul_f32 v[44:45], v[44:45], v[50:51]
	s_nop 0
	v_pk_fma_f32 v[44:45], v[46:47], v[44:45], 1.0 op_sel_hi:[1,1,0] neg_lo:[1,0,0] neg_hi:[1,0,0]
	s_nop 0
	v_bfi_b32 v43, s17, v45, v43
	v_bfi_b32 v42, s17, v44, v42
	v_pk_add_f32 v[42:43], v[42:43], 1.0 op_sel_hi:[1,0]
	s_nop 0
	v_pk_mul_f32 v[38:39], v[38:39], v[42:43]
	s_nop 0
	v_pk_mul_f32 v[28:29], v[28:29], v[38:39]
	s_nop 0
	v_pk_mul_f32 v[28:29], v[32:33], v[28:29]
	s_nop 0
	v_cvt_pk_bf16_f32 v27, v28, v29
	global_store_dwordx2 v[30:31], v[26:27], off offset:1056
	s_nop 0
	s_waitcnt vmcnt(5)
	v_lshlrev_b32_e32 v38, 16, v242
	v_and_b32_e32 v39, 0xffff0000, v242
	v_pk_mul_f32 v[42:43], v[38:39], s[18:19] op_sel_hi:[1,0]
	v_lshlrev_b32_e32 v40, 16, v244
	v_fma_f32 v27, |v42|, s3, 1.0
	v_rcp_f32_e32 v44, v27
	v_mul_f32_e64 v27, |v42|, s16
	v_mul_f32_e64 v27, |v42|, v27
	v_exp_f32_e32 v46, v27
	v_mul_f32_e32 v27, 0xbfb8aa3b, v40
	v_exp_f32_e32 v27, v27
	v_and_b32_e32 v41, 0xffff0000, v244
	v_pk_mul_f32 v[38:39], v[38:39], 0.5 op_sel_hi:[1,0]
	v_lshlrev_b32_e32 v28, 16, v243
	v_add_f32_e32 v27, 1.0, v27
	v_rcp_f32_e32 v48, v27
	v_fma_f32 v27, |v43|, s3, 1.0
	v_rcp_f32_e32 v45, v27
	v_mul_f32_e64 v27, |v43|, s16
	v_mul_f32_e64 v27, |v43|, v27
	v_exp_f32_e32 v47, v27
	v_pk_add_f32 v[22:23], v[22:23], v[240:241] op_sel_hi:[1,0]
	v_mul_f32_e32 v27, 0xbfb8aa3b, v41
	v_pk_fma_f32 v[50:51], v[44:45], s[20:21], v[62:63] op_sel_hi:[1,0,0]
	v_exp_f32_e32 v27, v27
	v_pk_fma_f32 v[50:51], v[44:45], v[50:51], s[22:23] op_sel_hi:[1,1,0]
	v_and_b32_e32 v29, 0xffff0000, v243
	v_pk_fma_f32 v[50:51], v[44:45], v[50:51], s[24:25] op_sel_hi:[1,1,0]
	v_add_f32_e32 v27, 1.0, v27
	v_pk_fma_f32 v[50:51], v[44:45], v[50:51], s[26:27] op_sel_hi:[1,1,0]
	v_rcp_f32_e32 v49, v27
	v_pk_mul_f32 v[44:45], v[44:45], v[50:51]
	v_lshlrev_b32_e32 v32, 16, v245
	v_pk_fma_f32 v[44:45], v[46:47], v[44:45], 1.0 op_sel_hi:[1,1,0] neg_lo:[1,0,0] neg_hi:[1,0,0]
	v_and_b32_e32 v33, 0xffff0000, v245
	v_bfi_b32 v43, s17, v45, v43
	v_bfi_b32 v42, s17, v44, v42
	v_pk_add_f32 v[42:43], v[42:43], 1.0 op_sel_hi:[1,0]
	v_pk_add_f32 v[24:25], v[24:25], v[240:241] op_sel_hi:[1,0]
	v_pk_mul_f32 v[38:39], v[38:39], v[42:43]
	s_nop 0
	v_pk_mul_f32 v[22:23], v[22:23], v[38:39]
	v_pk_mul_f32 v[38:39], v[48:49], v[40:41]
	s_nop 0
	v_pk_mul_f32 v[22:23], v[38:39], v[22:23]
	v_pk_mul_f32 v[38:39], v[28:29], s[18:19] op_sel_hi:[1,0]
	v_cvt_pk_bf16_f32 v22, v22, v23
	v_fma_f32 v23, |v38|, s3, 1.0
	v_rcp_f32_e32 v40, v23
	v_mul_f32_e64 v23, |v38|, s16
	v_mul_f32_e64 v23, |v38|, v23
	v_exp_f32_e32 v42, v23
	v_mul_f32_e32 v23, 0xbfb8aa3b, v32
	v_exp_f32_e32 v23, v23
	v_pk_mul_f32 v[28:29], v[28:29], 0.5 op_sel_hi:[1,0]
	v_add_f32_e32 v23, 1.0, v23
	v_rcp_f32_e32 v44, v23
	v_fma_f32 v23, |v39|, s3, 1.0
	v_rcp_f32_e32 v41, v23
	v_mul_f32_e64 v23, |v39|, s16
	v_mul_f32_e64 v23, |v39|, v23
	v_exp_f32_e32 v43, v23
	v_mul_f32_e32 v23, 0xbfb8aa3b, v33
	v_pk_fma_f32 v[46:47], v[40:41], s[20:21], v[62:63] op_sel_hi:[1,0,0]
	v_exp_f32_e32 v23, v23
	v_pk_fma_f32 v[46:47], v[40:41], v[46:47], s[22:23] op_sel_hi:[1,1,0]
	v_add_f32_e32 v23, 1.0, v23
	v_pk_fma_f32 v[46:47], v[40:41], v[46:47], s[24:25] op_sel_hi:[1,1,0]
	v_rcp_f32_e32 v45, v23
	v_pk_fma_f32 v[46:47], v[40:41], v[46:47], s[26:27] op_sel_hi:[1,1,0]
	v_pk_mul_f32 v[26:27], v[44:45], v[32:33]
	v_pk_mul_f32 v[40:41], v[40:41], v[46:47]
	s_nop 0
	v_pk_fma_f32 v[40:41], v[42:43], v[40:41], 1.0 op_sel_hi:[1,1,0] neg_lo:[1,0,0] neg_hi:[1,0,0]
	s_nop 0
	v_bfi_b32 v39, s17, v41, v39
	v_bfi_b32 v38, s17, v40, v38
	v_pk_add_f32 v[38:39], v[38:39], 1.0 op_sel_hi:[1,0]
	s_nop 0
	v_pk_mul_f32 v[28:29], v[28:29], v[38:39]
	s_nop 0
	v_pk_mul_f32 v[24:25], v[24:25], v[28:29]
	s_nop 0
	v_pk_mul_f32 v[24:25], v[26:27], v[24:25]
	s_nop 0
	v_cvt_pk_bf16_f32 v23, v24, v25
	global_store_dwordx2 v[30:31], v[22:23], off offset:1088
	s_nop 0
	s_waitcnt vmcnt(3)
	v_lshlrev_b32_e32 v28, 16, v248
	v_and_b32_e32 v29, 0xffff0000, v248
	v_pk_mul_f32 v[34:35], v[28:29], s[18:19] op_sel_hi:[1,0]
	v_lshlrev_b32_e32 v32, 16, v250
	v_fma_f32 v23, |v34|, s3, 1.0
	v_rcp_f32_e32 v36, v23
	v_mul_f32_e64 v23, |v34|, s16
	v_mul_f32_e64 v23, |v34|, v23
	v_exp_f32_e32 v38, v23
	v_mul_f32_e32 v23, 0xbfb8aa3b, v32
	v_exp_f32_e32 v23, v23
	v_and_b32_e32 v33, 0xffff0000, v250
	v_pk_mul_f32 v[28:29], v[28:29], 0.5 op_sel_hi:[1,0]
	v_lshlrev_b32_e32 v24, 16, v249
	v_add_f32_e32 v23, 1.0, v23
	v_rcp_f32_e32 v40, v23
	v_fma_f32 v23, |v35|, s3, 1.0
	v_rcp_f32_e32 v37, v23
	v_mul_f32_e64 v23, |v35|, s16
	v_mul_f32_e64 v23, |v35|, v23
	v_exp_f32_e32 v39, v23
	v_pk_add_f32 v[18:19], v[18:19], v[246:247] op_sel_hi:[1,0]
	v_mul_f32_e32 v23, 0xbfb8aa3b, v33
	v_pk_fma_f32 v[42:43], v[36:37], s[20:21], v[62:63] op_sel_hi:[1,0,0]
	v_exp_f32_e32 v23, v23
	v_pk_fma_f32 v[42:43], v[36:37], v[42:43], s[22:23] op_sel_hi:[1,1,0]
	v_and_b32_e32 v25, 0xffff0000, v249
	v_pk_fma_f32 v[42:43], v[36:37], v[42:43], s[24:25] op_sel_hi:[1,1,0]
	v_add_f32_e32 v23, 1.0, v23
	v_pk_fma_f32 v[42:43], v[36:37], v[42:43], s[26:27] op_sel_hi:[1,1,0]
	v_rcp_f32_e32 v41, v23
	v_pk_mul_f32 v[36:37], v[36:37], v[42:43]
	v_lshlrev_b32_e32 v26, 16, v251
	v_pk_fma_f32 v[36:37], v[38:39], v[36:37], 1.0 op_sel_hi:[1,1,0] neg_lo:[1,0,0] neg_hi:[1,0,0]
	v_and_b32_e32 v27, 0xffff0000, v251
	v_bfi_b32 v35, s17, v37, v35
	v_bfi_b32 v34, s17, v36, v34
	v_pk_add_f32 v[34:35], v[34:35], 1.0 op_sel_hi:[1,0]
	v_pk_add_f32 v[20:21], v[20:21], v[246:247] op_sel_hi:[1,0]
	v_pk_mul_f32 v[28:29], v[28:29], v[34:35]
	s_nop 0
	v_pk_mul_f32 v[18:19], v[18:19], v[28:29]
	v_pk_mul_f32 v[28:29], v[40:41], v[32:33]
	s_nop 0
	v_pk_mul_f32 v[18:19], v[28:29], v[18:19]
	v_pk_mul_f32 v[28:29], v[24:25], s[18:19] op_sel_hi:[1,0]
	v_cvt_pk_bf16_f32 v18, v18, v19
	v_fma_f32 v19, |v28|, s3, 1.0
	v_rcp_f32_e32 v32, v19
	v_mul_f32_e64 v19, |v28|, s16
	v_mul_f32_e64 v19, |v28|, v19
	v_exp_f32_e32 v34, v19
	v_mul_f32_e32 v19, 0xbfb8aa3b, v26
	v_exp_f32_e32 v19, v19
	v_pk_mul_f32 v[24:25], v[24:25], 0.5 op_sel_hi:[1,0]
	v_add_f32_e32 v19, 1.0, v19
	v_rcp_f32_e32 v36, v19
	v_fma_f32 v19, |v29|, s3, 1.0
	v_rcp_f32_e32 v33, v19
	v_mul_f32_e64 v19, |v29|, s16
	v_mul_f32_e64 v19, |v29|, v19
	v_exp_f32_e32 v35, v19
	v_mul_f32_e32 v19, 0xbfb8aa3b, v27
	v_pk_fma_f32 v[38:39], v[32:33], s[20:21], v[62:63] op_sel_hi:[1,0,0]
	v_exp_f32_e32 v19, v19
	v_pk_fma_f32 v[38:39], v[32:33], v[38:39], s[22:23] op_sel_hi:[1,1,0]
	v_add_f32_e32 v19, 1.0, v19
	v_pk_fma_f32 v[38:39], v[32:33], v[38:39], s[24:25] op_sel_hi:[1,1,0]
	v_rcp_f32_e32 v37, v19
	v_pk_fma_f32 v[38:39], v[32:33], v[38:39], s[26:27] op_sel_hi:[1,1,0]
	v_pk_mul_f32 v[22:23], v[36:37], v[26:27]
	v_pk_mul_f32 v[32:33], v[32:33], v[38:39]
	s_nop 0
	v_pk_fma_f32 v[32:33], v[34:35], v[32:33], 1.0 op_sel_hi:[1,1,0] neg_lo:[1,0,0] neg_hi:[1,0,0]
	s_nop 0
	v_bfi_b32 v29, s17, v33, v29
	v_bfi_b32 v28, s17, v32, v28
	v_pk_add_f32 v[28:29], v[28:29], 1.0 op_sel_hi:[1,0]
	s_nop 0
	v_pk_mul_f32 v[24:25], v[24:25], v[28:29]
	s_nop 0
	v_pk_mul_f32 v[20:21], v[20:21], v[24:25]
	s_nop 0
	v_pk_mul_f32 v[20:21], v[22:23], v[20:21]
	v_or_b32_e32 v22, 48, v66
	v_cvt_pk_bf16_f32 v19, v20, v21
	global_store_dwordx2 v[30:31], v[18:19], off offset:1120
	v_mad_i64_i32 v[18:19], s[0:1], v22, s78, v[68:69]
	v_lshl_add_u64 v[18:19], v[18:19], 0, s[34:35]
	v_lshl_add_u64 v[20:21], v[18:19], 0, v[0:1]
	global_load_dwordx2 v[26:27], v[20:21], off offset:2048
	v_add_co_u32_e32 v18, vcc, s2, v20
	global_load_dword v24, v[64:65], off offset:192
	s_nop 0
	v_addc_co_u32_e32 v19, vcc, 0, v21, vcc
	global_load_dwordx2 v[192:193], v[18:19], off
	global_load_dword v194, v[64:65], off offset:192
	global_load_dwordx2 v[196:197], v[20:21], off offset:2080
	global_load_dwordx2 v[198:199], v[18:19], off offset:32
	global_load_dword v200, v[64:65], off offset:192
	global_load_dwordx2 v[202:203], v[20:21], off offset:2112
	global_load_dwordx2 v[204:205], v[18:19], off offset:64
	global_load_dword v206, v[64:65], off offset:192
	global_load_dwordx2 v[208:209], v[20:21], off offset:2144
	global_load_dwordx2 v[210:211], v[18:19], off offset:96
	v_ashrrev_i32_e32 v23, 31, v22
	s_waitcnt vmcnt(9)
	v_lshlrev_b32_e32 v30, 16, v26
	v_and_b32_e32 v31, 0xffff0000, v26
	v_pk_mul_f32 v[34:35], v[30:31], s[18:19] op_sel_hi:[1,0]
	v_pk_mul_f32 v[30:31], v[30:31], 0.5 op_sel_hi:[1,0]
	v_fma_f32 v25, |v34|, s3, 1.0
	v_rcp_f32_e32 v36, v25
	v_mul_f32_e64 v25, |v34|, s16
	v_lshlrev_b32_e32 v32, 16, v192
	v_mul_f32_e64 v25, |v34|, v25
	v_exp_f32_e32 v38, v25
	v_mul_f32_e32 v25, 0xbfb8aa3b, v32
	v_exp_f32_e32 v25, v25
	v_and_b32_e32 v33, 0xffff0000, v192
	v_lshlrev_b32_e32 v28, 16, v193
	v_and_b32_e32 v29, 0xffff0000, v193
	v_add_f32_e32 v25, 1.0, v25
	v_rcp_f32_e32 v40, v25
	v_fma_f32 v25, |v35|, s3, 1.0
	v_rcp_f32_e32 v37, v25
	v_mul_f32_e64 v25, |v35|, s16
	v_mul_f32_e64 v25, |v35|, v25
	v_exp_f32_e32 v39, v25
	v_pk_add_f32 v[14:15], v[14:15], v[24:25] op_sel_hi:[1,0]
	v_mul_f32_e32 v25, 0xbfb8aa3b, v33
	v_pk_fma_f32 v[42:43], v[36:37], s[20:21], v[62:63] op_sel_hi:[1,0,0]
	v_exp_f32_e32 v25, v25
	v_pk_fma_f32 v[42:43], v[36:37], v[42:43], s[22:23] op_sel_hi:[1,1,0]
	v_add_f32_e32 v25, 1.0, v25
	v_pk_fma_f32 v[42:43], v[36:37], v[42:43], s[24:25] op_sel_hi:[1,1,0]
	v_rcp_f32_e32 v41, v25
	v_pk_fma_f32 v[42:43], v[36:37], v[42:43], s[26:27] op_sel_hi:[1,1,0]
	s_nop 0
	v_pk_mul_f32 v[36:37], v[36:37], v[42:43]
	s_nop 0
	v_pk_fma_f32 v[36:37], v[38:39], v[36:37], 1.0 op_sel_hi:[1,1,0] neg_lo:[1,0,0] neg_hi:[1,0,0]
	s_nop 0
	v_bfi_b32 v35, s17, v37, v35
	v_bfi_b32 v34, s17, v36, v34
	v_pk_add_f32 v[34:35], v[34:35], 1.0 op_sel_hi:[1,0]
	s_nop 0
	v_pk_mul_f32 v[30:31], v[30:31], v[34:35]
	s_nop 0
	v_pk_mul_f32 v[14:15], v[14:15], v[30:31]
	v_pk_mul_f32 v[30:31], v[40:41], v[32:33]
	s_nop 0
	v_pk_mul_f32 v[14:15], v[30:31], v[14:15]
	s_nop 0
	v_cvt_pk_bf16_f32 v26, v14, v15
	v_lshlrev_b32_e32 v14, 16, v27
	v_and_b32_e32 v15, 0xffff0000, v27
	v_pk_mul_f32 v[30:31], v[14:15], s[18:19] op_sel_hi:[1,0]
	v_pk_mul_f32 v[14:15], v[14:15], 0.5 op_sel_hi:[1,0]
	v_fma_f32 v25, |v30|, s3, 1.0
	v_rcp_f32_e32 v32, v25
	v_mul_f32_e64 v25, |v30|, s16
	v_mul_f32_e64 v25, |v30|, v25
	v_exp_f32_e32 v34, v25
	v_mul_f32_e32 v25, 0xbfb8aa3b, v28
	v_exp_f32_e32 v25, v25
	s_nop 0
	v_add_f32_e32 v25, 1.0, v25
	v_rcp_f32_e32 v36, v25
	v_fma_f32 v25, |v31|, s3, 1.0
	v_rcp_f32_e32 v33, v25
	v_mul_f32_e64 v25, |v31|, s16
	v_mul_f32_e64 v25, |v31|, v25
	v_exp_f32_e32 v35, v25
	v_pk_fma_f32 v[38:39], v[32:33], s[20:21], v[62:63] op_sel_hi:[1,0,0]
	v_pk_add_f32 v[16:17], v[16:17], v[24:25] op_sel_hi:[1,0]
	v_pk_fma_f32 v[38:39], v[32:33], v[38:39], s[22:23] op_sel_hi:[1,1,0]
	s_nop 0
	v_pk_fma_f32 v[38:39], v[32:33], v[38:39], s[24:25] op_sel_hi:[1,1,0]
	s_nop 0
	v_pk_fma_f32 v[38:39], v[32:33], v[38:39], s[26:27] op_sel_hi:[1,1,0]
	s_nop 0
	v_pk_mul_f32 v[32:33], v[32:33], v[38:39]
	s_nop 0
	v_pk_fma_f32 v[32:33], v[34:35], v[32:33], 1.0 op_sel_hi:[1,1,0] neg_lo:[1,0,0] neg_hi:[1,0,0]
	s_nop 0
	v_bfi_b32 v31, s17, v33, v31
	v_bfi_b32 v30, s17, v32, v30
	v_pk_add_f32 v[30:31], v[30:31], 1.0 op_sel_hi:[1,0]
	s_nop 0
	v_pk_mul_f32 v[14:15], v[14:15], v[30:31]
	s_nop 0
	v_pk_mul_f32 v[14:15], v[16:17], v[14:15]
	v_mul_f32_e32 v16, 0xbfb8aa3b, v29
	v_exp_f32_e32 v16, v16
	s_nop 0
	v_add_f32_e32 v16, 1.0, v16
	v_rcp_f32_e32 v37, v16
	s_nop 0
	v_pk_mul_f32 v[16:17], v[36:37], v[28:29]
	s_nop 0
	v_pk_mul_f32 v[14:15], v[16:17], v[14:15]
	s_nop 0
	v_cvt_pk_bf16_f32 v27, v14, v15
	v_lshlrev_b64 v[14:15], 11, v[22:23]
	v_lshl_add_u64 v[14:15], s[60:61], 0, v[14:15]
	v_lshl_add_u64 v[14:15], v[14:15], 0, s[34:35]
	v_lshl_add_u64 v[14:15], v[14:15], 0, v[0:1]
	global_store_dwordx2 v[14:15], v[26:27], off offset:1024
	v_readlane_b32 s34, v254, 25
	v_readlane_b32 s35, v254, 26
	s_waitcnt vmcnt(7)
	v_pk_add_f32 v[10:11], v[10:11], v[194:195] op_sel_hi:[1,0]
	v_lshlrev_b32_e32 v24, 16, v196
	v_and_b32_e32 v25, 0xffff0000, v196
	v_pk_mul_f32 v[28:29], v[24:25], s[18:19] op_sel_hi:[1,0]
	v_lshlrev_b32_e32 v26, 16, v198
	v_fma_f32 v16, |v28|, s3, 1.0
	v_rcp_f32_e32 v30, v16
	v_mul_f32_e64 v16, |v28|, s16
	v_mul_f32_e64 v16, |v28|, v16
	v_exp_f32_e32 v32, v16
	v_mul_f32_e32 v16, 0xbfb8aa3b, v26
	v_exp_f32_e32 v16, v16
	v_and_b32_e32 v27, 0xffff0000, v198
	v_pk_mul_f32 v[24:25], v[24:25], 0.5 op_sel_hi:[1,0]
	v_lshlrev_b32_e32 v22, 16, v199
	v_add_f32_e32 v16, 1.0, v16
	v_rcp_f32_e32 v34, v16
	v_fma_f32 v16, |v29|, s3, 1.0
	v_rcp_f32_e32 v31, v16
	v_mul_f32_e64 v16, |v29|, s16
	v_mul_f32_e64 v16, |v29|, v16
	v_exp_f32_e32 v33, v16
	v_mul_f32_e32 v16, 0xbfb8aa3b, v27
	v_pk_fma_f32 v[36:37], v[30:31], s[20:21], v[62:63] op_sel_hi:[1,0,0]
	v_exp_f32_e32 v16, v16
	v_pk_fma_f32 v[36:37], v[30:31], v[36:37], s[22:23] op_sel_hi:[1,1,0]
	v_and_b32_e32 v23, 0xffff0000, v199
	v_pk_fma_f32 v[36:37], v[30:31], v[36:37], s[24:25] op_sel_hi:[1,1,0]
	v_add_f32_e32 v16, 1.0, v16
	v_pk_fma_f32 v[36:37], v[30:31], v[36:37], s[26:27] op_sel_hi:[1,1,0]
	v_rcp_f32_e32 v35, v16
	v_pk_mul_f32 v[30:31], v[30:31], v[36:37]
	v_lshlrev_b32_e32 v16, 16, v197
	v_pk_fma_f32 v[30:31], v[32:33], v[30:31], 1.0 op_sel_hi:[1,1,0] neg_lo:[1,0,0] neg_hi:[1,0,0]
	v_and_b32_e32 v17, 0xffff0000, v197
	v_bfi_b32 v29, s17, v31, v29
	v_bfi_b32 v28, s17, v30, v28
	v_pk_add_f32 v[28:29], v[28:29], 1.0 op_sel_hi:[1,0]
	v_pk_add_f32 v[12:13], v[12:13], v[194:195] op_sel_hi:[1,0]
	v_pk_mul_f32 v[24:25], v[24:25], v[28:29]
	v_mul_f32_e32 v0, 0xbfb8aa3b, v23
	v_pk_mul_f32 v[10:11], v[10:11], v[24:25]
	v_pk_mul_f32 v[24:25], v[34:35], v[26:27]
	v_exp_f32_e32 v0, v0
	v_pk_mul_f32 v[10:11], v[24:25], v[10:11]
	v_pk_mul_f32 v[24:25], v[16:17], s[18:19] op_sel_hi:[1,0]
	v_cvt_pk_bf16_f32 v10, v10, v11
	v_fma_f32 v11, |v24|, s3, 1.0
	v_rcp_f32_e32 v26, v11
	v_mul_f32_e64 v11, |v24|, s16
	v_mul_f32_e64 v11, |v24|, v11
	v_exp_f32_e32 v28, v11
	v_mul_f32_e32 v11, 0xbfb8aa3b, v22
	v_exp_f32_e32 v11, v11
	v_add_f32_e32 v0, 1.0, v0
	v_rcp_f32_e32 v31, v0
	v_pk_mul_f32 v[16:17], v[16:17], 0.5 op_sel_hi:[1,0]
	v_add_f32_e32 v11, 1.0, v11
	v_rcp_f32_e32 v30, v11
	v_fma_f32 v11, |v25|, s3, 1.0
	v_rcp_f32_e32 v27, v11
	v_mul_f32_e64 v11, |v25|, s16
	v_mul_f32_e64 v11, |v25|, v11
	v_exp_f32_e32 v29, v11
	v_pk_fma_f32 v[32:33], v[26:27], s[20:21], v[62:63] op_sel_hi:[1,0,0]
	s_nop 0
	v_pk_fma_f32 v[32:33], v[26:27], v[32:33], s[22:23] op_sel_hi:[1,1,0]
	s_nop 0
	v_pk_fma_f32 v[32:33], v[26:27], v[32:33], s[24:25] op_sel_hi:[1,1,0]
	s_nop 0
	v_pk_fma_f32 v[32:33], v[26:27], v[32:33], s[26:27] op_sel_hi:[1,1,0]
	s_nop 0
	v_pk_mul_f32 v[26:27], v[26:27], v[32:33]
	s_nop 0
	v_pk_fma_f32 v[26:27], v[28:29], v[26:27], 1.0 op_sel_hi:[1,1,0] neg_lo:[1,0,0] neg_hi:[1,0,0]
	s_nop 0
	v_bfi_b32 v25, s17, v27, v25
	v_bfi_b32 v24, s17, v26, v24
	v_pk_add_f32 v[24:25], v[24:25], 1.0 op_sel_hi:[1,0]
	s_nop 0
	v_pk_mul_f32 v[16:17], v[16:17], v[24:25]
	s_nop 0
	v_pk_mul_f32 v[12:13], v[12:13], v[16:17]
	v_pk_mul_f32 v[16:17], v[30:31], v[22:23]
	s_nop 0
	v_pk_mul_f32 v[12:13], v[16:17], v[12:13]
	s_nop 0
	v_cvt_pk_bf16_f32 v11, v12, v13
	global_store_dwordx2 v[14:15], v[10:11], off offset:1056
	s_nop 0
	s_waitcnt vmcnt(5)
; template <int TRANS, class AP, class BP, class Epi>
; DI void mfma_gemm_tile(const AP& aptr, const BP& bptr, int m0, int n0, int K, const Epi& epi, bf16* lds) {
;     ...
;   asm volatile("s_waitcnt vmcnt(0)" ::: "memory");
;   __syncthreads();
	v_pk_add_f32 v[6:7], v[6:7], v[200:201] op_sel_hi:[1,0]
	v_lshlrev_b32_e32 v16, 16, v202
	v_and_b32_e32 v17, 0xffff0000, v202
	v_pk_mul_f32 v[24:25], v[16:17], s[18:19] op_sel_hi:[1,0]
	v_lshlrev_b32_e32 v22, 16, v204
	v_fma_f32 v10, |v24|, s3, 1.0
	v_rcp_f32_e32 v26, v10
	v_mul_f32_e64 v10, |v24|, s16
	v_mul_f32_e64 v10, |v24|, v10
	v_exp_f32_e32 v28, v10
	v_mul_f32_e32 v10, 0xbfb8aa3b, v22
	v_exp_f32_e32 v10, v10
	v_and_b32_e32 v23, 0xffff0000, v204
	v_pk_mul_f32 v[16:17], v[16:17], 0.5 op_sel_hi:[1,0]
	v_lshlrev_b32_e32 v12, 16, v205
	v_add_f32_e32 v10, 1.0, v10
	v_rcp_f32_e32 v30, v10
	v_fma_f32 v10, |v25|, s3, 1.0
	v_rcp_f32_e32 v27, v10
	v_mul_f32_e64 v10, |v25|, s16
	v_mul_f32_e64 v10, |v25|, v10
	v_exp_f32_e32 v29, v10
	v_mul_f32_e32 v10, 0xbfb8aa3b, v23
	v_pk_fma_f32 v[32:33], v[26:27], s[20:21], v[62:63] op_sel_hi:[1,0,0]
	v_exp_f32_e32 v10, v10
	v_pk_fma_f32 v[32:33], v[26:27], v[32:33], s[22:23] op_sel_hi:[1,1,0]
	v_and_b32_e32 v13, 0xffff0000, v205
	v_pk_fma_f32 v[32:33], v[26:27], v[32:33], s[24:25] op_sel_hi:[1,1,0]
	v_add_f32_e32 v10, 1.0, v10
	v_pk_fma_f32 v[32:33], v[26:27], v[32:33], s[26:27] op_sel_hi:[1,1,0]
	v_rcp_f32_e32 v31, v10
	v_pk_mul_f32 v[26:27], v[26:27], v[32:33]
	v_lshlrev_b32_e32 v10, 16, v203
	v_pk_fma_f32 v[26:27], v[28:29], v[26:27], 1.0 op_sel_hi:[1,1,0] neg_lo:[1,0,0] neg_hi:[1,0,0]
	v_and_b32_e32 v11, 0xffff0000, v203
	v_bfi_b32 v25, s17, v27, v25
	v_bfi_b32 v24, s17, v26, v24
	v_pk_add_f32 v[24:25], v[24:25], 1.0 op_sel_hi:[1,0]
	v_pk_add_f32 v[8:9], v[8:9], v[200:201] op_sel_hi:[1,0]
	v_pk_mul_f32 v[16:17], v[16:17], v[24:25]
	v_mul_f32_e32 v0, 0xbfb8aa3b, v13
	v_pk_mul_f32 v[6:7], v[6:7], v[16:17]
	v_pk_mul_f32 v[16:17], v[30:31], v[22:23]
	v_exp_f32_e32 v0, v0
	v_pk_mul_f32 v[6:7], v[16:17], v[6:7]
	v_pk_mul_f32 v[16:17], v[10:11], s[18:19] op_sel_hi:[1,0]
	v_cvt_pk_bf16_f32 v6, v6, v7
	v_fma_f32 v7, |v16|, s3, 1.0
	v_rcp_f32_e32 v22, v7
	v_mul_f32_e64 v7, |v16|, s16
	v_mul_f32_e64 v7, |v16|, v7
	v_exp_f32_e32 v24, v7
	v_mul_f32_e32 v7, 0xbfb8aa3b, v12
	v_exp_f32_e32 v7, v7
	v_add_f32_e32 v0, 1.0, v0
	v_rcp_f32_e32 v27, v0
	v_pk_mul_f32 v[10:11], v[10:11], 0.5 op_sel_hi:[1,0]
	v_add_f32_e32 v7, 1.0, v7
	v_rcp_f32_e32 v26, v7
	v_fma_f32 v7, |v17|, s3, 1.0
	v_rcp_f32_e32 v23, v7
	v_mul_f32_e64 v7, |v17|, s16
	v_mul_f32_e64 v7, |v17|, v7
	v_exp_f32_e32 v25, v7
	v_pk_fma_f32 v[28:29], v[22:23], s[20:21], v[62:63] op_sel_hi:[1,0,0]
	s_nop 0
	v_pk_fma_f32 v[28:29], v[22:23], v[28:29], s[22:23] op_sel_hi:[1,1,0]
	s_nop 0
	v_pk_fma_f32 v[28:29], v[22:23], v[28:29], s[24:25] op_sel_hi:[1,1,0]
	s_nop 0
	v_pk_fma_f32 v[28:29], v[22:23], v[28:29], s[26:27] op_sel_hi:[1,1,0]
	s_nop 0
	v_pk_mul_f32 v[22:23], v[22:23], v[28:29]
	s_nop 0
	v_pk_fma_f32 v[22:23], v[24:25], v[22:23], 1.0 op_sel_hi:[1,1,0] neg_lo:[1,0,0] neg_hi:[1,0,0]
	s_nop 0
	v_bfi_b32 v17, s17, v23, v17
	v_bfi_b32 v16, s17, v22, v16
	v_pk_add_f32 v[16:17], v[16:17], 1.0 op_sel_hi:[1,0]
	s_nop 0
	v_pk_mul_f32 v[10:11], v[10:11], v[16:17]
	s_nop 0
	v_pk_mul_f32 v[8:9], v[8:9], v[10:11]
	v_pk_mul_f32 v[10:11], v[26:27], v[12:13]
	s_nop 0
	v_pk_mul_f32 v[8:9], v[10:11], v[8:9]
	s_nop 0
	v_cvt_pk_bf16_f32 v7, v8, v9
	global_store_dwordx2 v[14:15], v[6:7], off offset:1088
	s_nop 0
	s_waitcnt vmcnt(3)
	v_pk_add_f32 v[2:3], v[2:3], v[206:207] op_sel_hi:[1,0]
	v_lshlrev_b32_e32 v10, 16, v208
	v_and_b32_e32 v11, 0xffff0000, v208
	v_pk_mul_f32 v[16:17], v[10:11], s[18:19] op_sel_hi:[1,0]
	v_lshlrev_b32_e32 v12, 16, v210
	v_fma_f32 v6, |v16|, s3, 1.0
	v_rcp_f32_e32 v18, v6
	v_mul_f32_e64 v6, |v16|, s16
	v_mul_f32_e64 v6, |v16|, v6
	v_exp_f32_e32 v20, v6
	v_mul_f32_e32 v6, 0xbfb8aa3b, v12
	v_exp_f32_e32 v6, v6
	v_and_b32_e32 v13, 0xffff0000, v210
	v_pk_mul_f32 v[10:11], v[10:11], 0.5 op_sel_hi:[1,0]
	v_lshlrev_b32_e32 v8, 16, v211
	v_add_f32_e32 v6, 1.0, v6
	v_rcp_f32_e32 v22, v6
	v_fma_f32 v6, |v17|, s3, 1.0
	v_rcp_f32_e32 v19, v6
	v_mul_f32_e64 v6, |v17|, s16
	v_mul_f32_e64 v6, |v17|, v6
	v_exp_f32_e32 v21, v6
	v_mul_f32_e32 v6, 0xbfb8aa3b, v13
	v_pk_fma_f32 v[24:25], v[18:19], s[20:21], v[62:63] op_sel_hi:[1,0,0]
	v_exp_f32_e32 v6, v6
	v_pk_fma_f32 v[24:25], v[18:19], v[24:25], s[22:23] op_sel_hi:[1,1,0]
	v_and_b32_e32 v9, 0xffff0000, v211
	v_pk_fma_f32 v[24:25], v[18:19], v[24:25], s[24:25] op_sel_hi:[1,1,0]
	v_add_f32_e32 v6, 1.0, v6
	v_pk_fma_f32 v[24:25], v[18:19], v[24:25], s[26:27] op_sel_hi:[1,1,0]
	v_rcp_f32_e32 v23, v6
	v_pk_mul_f32 v[18:19], v[18:19], v[24:25]
	v_lshlrev_b32_e32 v6, 16, v209
	v_pk_fma_f32 v[18:19], v[20:21], v[18:19], 1.0 op_sel_hi:[1,1,0] neg_lo:[1,0,0] neg_hi:[1,0,0]
	v_and_b32_e32 v7, 0xffff0000, v209
	v_bfi_b32 v17, s17, v19, v17
	v_bfi_b32 v16, s17, v18, v16
	v_pk_add_f32 v[16:17], v[16:17], 1.0 op_sel_hi:[1,0]
	v_pk_add_f32 v[4:5], v[4:5], v[206:207] op_sel_hi:[1,0]
	v_pk_mul_f32 v[10:11], v[10:11], v[16:17]
	v_mul_f32_e32 v0, 0xbfb8aa3b, v9
	v_pk_mul_f32 v[2:3], v[2:3], v[10:11]
	v_pk_mul_f32 v[10:11], v[22:23], v[12:13]
	v_exp_f32_e32 v0, v0
	v_pk_mul_f32 v[2:3], v[10:11], v[2:3]
	v_pk_mul_f32 v[10:11], v[6:7], s[18:19] op_sel_hi:[1,0]
	v_cvt_pk_bf16_f32 v2, v2, v3
	v_fma_f32 v3, |v10|, s3, 1.0
	v_rcp_f32_e32 v12, v3
	v_mul_f32_e64 v3, |v10|, s16
	v_mul_f32_e64 v3, |v10|, v3
	v_exp_f32_e32 v16, v3
	v_mul_f32_e32 v3, 0xbfb8aa3b, v8
	v_exp_f32_e32 v3, v3
	v_add_f32_e32 v0, 1.0, v0
	v_rcp_f32_e32 v19, v0
	v_pk_mul_f32 v[6:7], v[6:7], 0.5 op_sel_hi:[1,0]
	v_add_f32_e32 v3, 1.0, v3
	v_rcp_f32_e32 v18, v3
	v_fma_f32 v3, |v11|, s3, 1.0
	v_rcp_f32_e32 v13, v3
	v_mul_f32_e64 v3, |v11|, s16
	v_mul_f32_e64 v3, |v11|, v3
	v_exp_f32_e32 v17, v3
	v_pk_fma_f32 v[20:21], v[12:13], s[20:21], v[62:63] op_sel_hi:[1,0,0]
	s_nop 0
	v_pk_fma_f32 v[20:21], v[12:13], v[20:21], s[22:23] op_sel_hi:[1,1,0]
	s_nop 0
	v_pk_fma_f32 v[20:21], v[12:13], v[20:21], s[24:25] op_sel_hi:[1,1,0]
	s_nop 0
	v_pk_fma_f32 v[20:21], v[12:13], v[20:21], s[26:27] op_sel_hi:[1,1,0]
	s_nop 0
	v_pk_mul_f32 v[12:13], v[12:13], v[20:21]
	s_nop 0
	v_pk_fma_f32 v[12:13], v[16:17], v[12:13], 1.0 op_sel_hi:[1,1,0] neg_lo:[1,0,0] neg_hi:[1,0,0]
	s_nop 0
	v_bfi_b32 v11, s17, v13, v11
	v_bfi_b32 v10, s17, v12, v10
	v_pk_add_f32 v[10:11], v[10:11], 1.0 op_sel_hi:[1,0]
	s_nop 0
	v_pk_mul_f32 v[6:7], v[6:7], v[10:11]
	s_nop 0
	v_pk_mul_f32 v[4:5], v[4:5], v[6:7]
	v_pk_mul_f32 v[6:7], v[18:19], v[8:9]
	s_nop 0
	v_pk_mul_f32 v[4:5], v[6:7], v[4:5]
	s_nop 0
	v_cvt_pk_bf16_f32 v3, v4, v5
	global_store_dwordx2 v[14:15], v[2:3], off offset:1120
	s_waitcnt vmcnt(0)
	s_waitcnt lgkmcnt(0)
	s_barrier
